# conv main loop with packed f32 FMA (2 channels x 16 tokens per thread, weights prefetched at item top); KV->Q up-proj fusion: KV last K-iteration prefetches Q unit first tiles (grid 256 only)
# speedup vs baseline: 1.0369x; 1.0046x over previous
;     __host__ __device__ bool next(int i, Unit& u) const {
;         const long L = (long)i * G + c; if (L >= nwg) return false;
;         int wgid = (int)L; { const int q = nwg / NXCD, r = nwg % NXCD, xcd = wgid % NXCD, off = wgid / NXCD; wgid = (xcd < r ? xcd * (q + 1) : r * (q + 1) + (xcd - r) * q) + off; }
;         const int nig = WGM * nN, gid = wgid / nig, fm = gid * WGM, gsz = (nM - fm) < WGM ? (nM - fm) : WGM;
;         u.pm = fm + ((wgid % nig) % gsz); u.pn = (wgid % nig) / gsz; return true;
; template <class Epi, class Sched>
; __device__ __forceinline__ void gemm_phase(LAS unsigned char* lds, const Gemm g, const Sched& S, const Epi& E) {
;     ...
;         const bool has_next = S.next(ui + 1, nxt);
;         const char* nA = has_next ? (const char*)g.A + (size_t)nxt.pm * tsA : cA; const char* nB = has_next ? (const char*)g.Bt + (size_t)nxt.pn * tsB : cB;
;         for (int t = 0; t < nt; t += 2) {
;             const bool last = (t == nt - 2);
;             const char* a1 = cA + (size_t)(t + 1) * kstep;
;             const char* a2 = last ? nA : cA + (size_t)(t + 2) * kstep; const char* b2 = last ? nB : cB + (size_t)(t + 2) * kstep;
;             const char* a3 = a2 + kstep; const char* b3 = b2 + kstep;
.Lkvq_a:
	s_cmpk_lg_i32 s58, 0x100
	s_cbranch_scc1 .Lkvq_skip
	s_add_i32 s98, s2, 64
	s_and_b32 s98, s98, 0xff
	s_cmpk_gt_i32 s98, 0xbf
	s_cbranch_scc1 .Lkvq_skip
	s_and_b32 s99, s98, 7
	s_lshr_b32 s98, s98, 3
	s_mul_i32 s99, s99, 24
	s_add_i32 s98, s99, s98
	s_mul_i32 s99, s98, 0x2ab
	s_lshr_b32 s99, s99, 15
	s_mul_i32 s100, s99, 48
	s_sub_i32 s98, s98, s100
	s_and_b32 s100, s98, 7
	s_lshl_b32 s99, s99, 3
	s_add_i32 s99, s99, s100
	s_lshr_b32 s98, s98, 3
	s_mul_i32 s100, s99, 0x288000
	s_add_u32 s34, s82, s100
	s_addc_u32 s35, s83, 0
	s_add_u32 s34, s34, 0x6c81800
	s_addc_u32 s35, s35, 0
	s_lshl_b32 s100, s98, 18
	s_add_u32 s67, s82, s100
	s_addc_u32 s31, s83, 0
	s_add_u32 s67, s67, 0x1900000
	s_addc_u32 s31, s31, 0
.Lkvq_skip:
	s_add_u32 s0, s8, 0x144080
	s_addc_u32 s1, s9, 0
	s_add_u32 s68, s6, 0x100
	v_mov_b32_e32 v0, 0
	s_addc_u32 s69, s7, 0
	s_mov_b32 s70, -2
	v_mov_b32_e32 v1, v0
	v_mov_b32_e32 v2, v0
	v_mov_b32_e32 v3, v0
	v_mov_b32_e32 v4, v0
	v_mov_b32_e32 v5, v0
	v_mov_b32_e32 v6, v0
	v_mov_b32_e32 v7, v0
	v_mov_b32_e32 v8, v0
	v_mov_b32_e32 v9, v0
	v_mov_b32_e32 v10, v0
	v_mov_b32_e32 v11, v0
	v_mov_b32_e32 v16, v0
	v_mov_b32_e32 v17, v0
	v_mov_b32_e32 v18, v0
	v_mov_b32_e32 v19, v0
	v_mov_b32_e32 v24, v0
	v_mov_b32_e32 v25, v0
	v_mov_b32_e32 v26, v0
	v_mov_b32_e32 v27, v0
	v_mov_b32_e32 v32, v0
	v_mov_b32_e32 v33, v0
	v_mov_b32_e32 v34, v0
	v_mov_b32_e32 v35, v0
	v_mov_b32_e32 v40, v0
	v_mov_b32_e32 v41, v0
	v_mov_b32_e32 v42, v0
	v_mov_b32_e32 v43, v0
	v_mov_b32_e32 v48, v0
	v_mov_b32_e32 v49, v0
	v_mov_b32_e32 v50, v0
	v_mov_b32_e32 v51, v0
	v_mov_b32_e32 v12, v0
	v_mov_b32_e32 v13, v0
	v_mov_b32_e32 v14, v0
	v_mov_b32_e32 v15, v0
	v_mov_b32_e32 v20, v0
	v_mov_b32_e32 v21, v0
	v_mov_b32_e32 v22, v0
	v_mov_b32_e32 v23, v0
	v_mov_b32_e32 v28, v0
	v_mov_b32_e32 v29, v0
	v_mov_b32_e32 v30, v0
	v_mov_b32_e32 v31, v0
	v_mov_b32_e32 v36, v0
	v_mov_b32_e32 v37, v0
	v_mov_b32_e32 v38, v0
	v_mov_b32_e32 v39, v0
	v_mov_b32_e32 v44, v0
	v_mov_b32_e32 v45, v0
	v_mov_b32_e32 v46, v0
	v_mov_b32_e32 v47, v0
	v_mov_b32_e32 v52, v0
	v_mov_b32_e32 v53, v0
	v_mov_b32_e32 v54, v0
	v_mov_b32_e32 v55, v0
	v_mov_b32_e32 v56, v0
	v_mov_b32_e32 v57, v0
	v_mov_b32_e32 v58, v0
	v_mov_b32_e32 v59, v0
	v_mov_b32_e32 v60, v0
	v_mov_b32_e32 v61, v0
	v_mov_b32_e32 v62, v0
	v_mov_b32_e32 v63, v0
	v_mov_b32_e32 v64, v0
	v_mov_b32_e32 v65, v0
	v_mov_b32_e32 v66, v0
	v_mov_b32_e32 v67, v0
	v_mov_b32_e32 v68, v0
	v_mov_b32_e32 v69, v0
	v_mov_b32_e32 v70, v0
	v_mov_b32_e32 v71, v0
	v_mov_b32_e32 v72, v0
	v_mov_b32_e32 v73, v0
	v_mov_b32_e32 v74, v0
	v_mov_b32_e32 v75, v0
	v_mov_b32_e32 v80, v0
	v_mov_b32_e32 v81, v0
	v_mov_b32_e32 v82, v0
	v_mov_b32_e32 v83, v0
	v_mov_b32_e32 v88, v0
	v_mov_b32_e32 v89, v0
	v_mov_b32_e32 v90, v0
	v_mov_b32_e32 v91, v0
	v_mov_b32_e32 v96, v0
	v_mov_b32_e32 v97, v0
	v_mov_b32_e32 v98, v0
	v_mov_b32_e32 v99, v0
	v_mov_b32_e32 v104, v0
	v_mov_b32_e32 v105, v0
	v_mov_b32_e32 v106, v0
	v_mov_b32_e32 v107, v0
	v_mov_b32_e32 v112, v0
	v_mov_b32_e32 v113, v0
	v_mov_b32_e32 v114, v0
	v_mov_b32_e32 v115, v0
	v_mov_b32_e32 v76, v0
	v_mov_b32_e32 v77, v0
	v_mov_b32_e32 v78, v0
	v_mov_b32_e32 v79, v0
	v_mov_b32_e32 v84, v0
	v_mov_b32_e32 v85, v0
	v_mov_b32_e32 v86, v0
	v_mov_b32_e32 v87, v0
	v_mov_b32_e32 v92, v0
	v_mov_b32_e32 v93, v0
	v_mov_b32_e32 v94, v0
	v_mov_b32_e32 v95, v0
	v_mov_b32_e32 v100, v0
	v_mov_b32_e32 v101, v0
	v_mov_b32_e32 v102, v0
	v_mov_b32_e32 v103, v0
	v_mov_b32_e32 v108, v0
	v_mov_b32_e32 v109, v0
	v_mov_b32_e32 v110, v0
	v_mov_b32_e32 v111, v0
	v_mov_b32_e32 v116, v0
	v_mov_b32_e32 v117, v0
	v_mov_b32_e32 v118, v0
	v_mov_b32_e32 v119, v0
	v_mov_b32_e32 v120, v0
	v_mov_b32_e32 v121, v0
	v_mov_b32_e32 v122, v0
	v_mov_b32_e32 v123, v0
	v_mov_b32_e32 v124, v0
	v_mov_b32_e32 v125, v0
	v_mov_b32_e32 v126, v0
	v_mov_b32_e32 v127, v0

; #define PG8_STAGE(bufoff, gbase, voff) do { _Pragma("unroll") for (int _i = 0; _i < 2; ++_i) \
;         __builtin_amdgcn_global_load_lds((const unsigned*)((const char*)(gbase) + (voff)[_i]), (LAS unsigned*)(lds + (bufoff) + ldsw + _i * 8192), 16, 0, 0); } while (0)
; #define PG8_WAIT_V(n) asm volatile("s_waitcnt vmcnt(" #n ")" ::: "memory")
; #define PG8_BAR __builtin_amdgcn_s_barrier()
; template <class Epi, class Sched>
; __device__ __forceinline__ void gemm_phase(LAS unsigned char* lds, const Gemm g, const Sched& S, const Epi& E) {
;     ...
;     const char* cA = (const char*)g.A + (size_t)cur.pm * tsA; const char* cB = (const char*)g.Bt + (size_t)cur.pn * tsB;
;     PG8_STAGE(PG8_SB(0, 0), cB, voffB); PG8_STAGE(PG8_SB(0, 1), cB + hsB, voffB); PG8_STAGE(PG8_SA(0, 0), cA, voffA); PG8_STAGE(PG8_SA(0, 1), cA + hsA, voffA);
;     if (wr == 1) PG8_BAR;
;     PG8_WAIT_V(2); PG8_BAR;
;     PG8_STAGE(PG8_SB(1, 0), cB + kstep, voffB); PG8_STAGE(PG8_SA(1, 0), cA + kstep, voffA); PG8_STAGE(PG8_SB(1, 1), cB + hsB + kstep, voffB);
;     PG8_WAIT_V(6); PG8_BAR;
.LBB0_428:
	s_andn2_b64 vcc, exec, s[0:1]
	s_cbranch_vccnz .LBB0_510
	s_cmpk_eq_i32 s58, 0x100
	s_cbranch_scc1 .Lkvq_pro
	s_add_u32 s41, s82, 0x6c81800
	s_addc_u32 s42, s83, 0
	s_add_u32 s43, s82, 0x1900000
	s_addc_u32 s44, s83, 0
	s_lshr_b32 s0, s4, 6
	s_ashr_i32 s7, s6, 31
	s_lshr_b32 s1, s4, 8
	s_lshl_b32 s45, s0, 10
	s_lshl_b64 s[8:9], s[6:7], 18
	s_add_u32 s8, s43, s8
	s_addc_u32 s9, s44, s9
	s_add_i32 s46, s45, 0
	s_add_i32 m0, s46, 0x10000
	s_mul_i32 s12, s90, 0x288000
	global_load_lds_dwordx4 v130, s[8:9]
	s_add_i32 m0, s46, 0x12000
	s_add_u32 s10, s8, 0x20000
	global_load_lds_dwordx4 v134, s[8:9]
	s_addc_u32 s11, s9, 0
	s_add_i32 m0, s46, 0x14000
	s_mul_hi_i32 s5, s90, 0x288000
	global_load_lds_dwordx4 v130, s[10:11]
	s_add_i32 m0, s46, 0x16000
	s_add_u32 s38, s41, s12
	s_addc_u32 s39, s42, s5
	s_add_i32 s47, s46, 0x2000
	global_load_lds_dwordx4 v134, s[10:11]
	s_mov_b32 m0, s46
	s_add_u32 s10, s38, 0x144000
	global_load_lds_dwordx4 v128, s[38:39]
	s_mov_b32 m0, s47
	s_addc_u32 s11, s39, 0
	s_add_i32 s48, s46, 0x4000
	global_load_lds_dwordx4 v132, s[38:39]
	s_mov_b32 m0, s48
	s_add_i32 s49, s46, 0x6000
	global_load_lds_dwordx4 v128, s[10:11]
	s_mov_b32 m0, s49
	v_mov_b32_e32 v137, 0
	global_load_lds_dwordx4 v132, s[10:11]
	v_mov_b32_e32 v131, v137
	v_mov_b32_e32 v135, v137
	v_mov_b32_e32 v129, v137
	v_mov_b32_e32 v133, v137
	s_cmp_eq_u32 s1, 1
	s_mov_b32 s50, 0
	v_lshl_add_u64 v[6:7], s[8:9], 0, v[130:131]
	v_lshl_add_u64 v[4:5], s[8:9], 0, v[134:135]
	v_lshl_add_u64 v[0:1], s[38:39], 0, v[128:129]
	s_cselect_b64 s[10:11], -1, 0
	s_cmp_lg_u32 s1, 1
	v_lshl_add_u64 v[2:3], s[38:39], 0, v[132:133]
	s_cbranch_scc1 .LBB0_431
	s_barrier

; #define PG8_STAGE(bufoff, gbase, voff) do { _Pragma("unroll") for (int _i = 0; _i < 2; ++_i) \
;         __builtin_amdgcn_global_load_lds((const unsigned*)((const char*)(gbase) + (voff)[_i]), (LAS unsigned*)(lds + (bufoff) + ldsw + _i * 8192), 16, 0, 0); } while (0)
; #define PG8_WAIT_V(n) asm volatile("s_waitcnt vmcnt(" #n ")" ::: "memory")
; #define PG8_BAR __builtin_amdgcn_s_barrier()
; template <class Epi, class Sched>
; __device__ __forceinline__ void gemm_phase(LAS unsigned char* lds, const Gemm g, const Sched& S, const Epi& E) {
;     ...
;     const char* cA = (const char*)g.A + (size_t)cur.pm * tsA; const char* cB = (const char*)g.Bt + (size_t)cur.pn * tsB;
;     PG8_STAGE(PG8_SB(0, 0), cB, voffB); PG8_STAGE(PG8_SB(0, 1), cB + hsB, voffB); PG8_STAGE(PG8_SA(0, 0), cA, voffA); PG8_STAGE(PG8_SA(0, 1), cA + hsA, voffA);
;     if (wr == 1) PG8_BAR;
;     PG8_WAIT_V(2); PG8_BAR;
;     PG8_STAGE(PG8_SB(1, 0), cB + kstep, voffB); PG8_STAGE(PG8_SA(1, 0), cA + kstep, voffA); PG8_STAGE(PG8_SB(1, 1), cB + hsB + kstep, voffB);
;     PG8_WAIT_V(6); PG8_BAR;
;     for (;;) {
.Lkvq_pro:
	s_add_u32 s41, s82, 0x6c81800
	s_addc_u32 s42, s83, 0
	s_add_u32 s43, s82, 0x1900000
	s_addc_u32 s44, s83, 0
	s_lshr_b32 s0, s4, 6
	s_ashr_i32 s7, s6, 31
	s_lshr_b32 s1, s4, 8
	s_lshl_b32 s45, s0, 10
	s_lshl_b64 s[8:9], s[6:7], 18
	s_add_u32 s8, s43, s8
	s_addc_u32 s9, s44, s9
	s_add_i32 s46, s45, 0
	s_add_i32 m0, s46, 0x10000
	s_mul_i32 s12, s90, 0x288000
	s_add_i32 m0, s46, 0x12000
	s_add_u32 s10, s8, 0x20000
	s_addc_u32 s11, s9, 0
	s_add_i32 m0, s46, 0x14000
	s_mul_hi_i32 s5, s90, 0x288000
	s_add_i32 m0, s46, 0x16000
	s_add_u32 s38, s41, s12
	s_addc_u32 s39, s42, s5
	s_add_i32 s47, s46, 0x2000
	s_mov_b32 m0, s46
	s_add_u32 s10, s38, 0x144000
	s_mov_b32 m0, s47
	s_addc_u32 s11, s39, 0
	s_add_i32 s48, s46, 0x4000
	s_mov_b32 m0, s48
	s_add_i32 s49, s46, 0x6000
	s_mov_b32 m0, s49
	v_mov_b32_e32 v137, 0
	v_mov_b32_e32 v131, v137
	v_mov_b32_e32 v135, v137
	v_mov_b32_e32 v129, v137
	v_mov_b32_e32 v133, v137
	s_cmp_eq_u32 s1, 1
	s_mov_b32 s50, 0
	v_lshl_add_u64 v[6:7], s[8:9], 0, v[130:131]
	v_lshl_add_u64 v[4:5], s[8:9], 0, v[134:135]
	v_lshl_add_u64 v[0:1], s[38:39], 0, v[128:129]
	s_cselect_b64 s[10:11], -1, 0
	s_cmp_lg_u32 s1, 1
	v_lshl_add_u64 v[2:3], s[38:39], 0, v[132:133]
	s_cbranch_scc1 .Lkvq_431
	s_barrier
.Lkvq_431:
	s_add_u32 s12, s82, 0xbd80000
	s_mov_b64 s[22:23], 0x80
	s_addc_u32 s13, s83, 0
	s_lshl_b32 s0, s0, 5
	s_add_i32 m0, s46, 0x18000
	v_lshl_add_u64 v[6:7], v[6:7], 0, s[22:23]
	s_lshl_b32 s51, s1, 6
	s_lshl_b32 s5, s1, 13
	s_and_b32 s7, s0, 0x60
	s_waitcnt vmcnt(2)
	s_barrier
	v_lshl_add_u64 v[4:5], v[4:5], 0, s[22:23]
	s_add_i32 m0, s46, 0x1a000
	s_add_i32 s53, s46, 0x8000
	s_add_i32 s54, s46, 0xa000
	v_lshl_add_u64 v[0:1], v[0:1], 0, s[22:23]
	s_mov_b32 m0, s53
	s_add_u32 s0, s8, 0x20080
	v_lshl_add_u64 v[0:1], v[2:3], 0, s[22:23]
	s_mov_b32 m0, s54
	s_addc_u32 s1, s9, 0
	s_add_i32 m0, s46, 0x1c000
	v_lshl_add_u64 v[0:1], s[0:1], 0, v[130:131]
	v_lshl_add_u64 v[0:1], s[0:1], 0, v[134:135]
	s_add_i32 m0, s46, 0x1e000
	s_cmpk_lt_u32 s4, 0x100
	v_lshlrev_b32_e32 v1, 2, v179
	v_lshl_or_b32 v0, v179, 6, v163
	v_and_b32_e32 v1, 32, v1
	v_bitop3_b32 v0, v0, s5, v1 bitop3:0xde
	s_waitcnt vmcnt(6)
	v_lshl_or_b32 v149, s7, 7, v164
	s_cselect_b64 s[26:27], -1, 0
	s_add_i32 s67, 0, 0x10000
	s_add_i32 s68, 0, 0x14000
	v_add_u32_e32 v182, 0, v0
	v_mbcnt_lo_u32_b32 v0, -1, 0
	v_lshl_add_u64 v[138:139], s[60:61], 0, v[136:137]
	s_ashr_i32 s55, s58, 31
	s_mov_b32 s64, s58
	s_ashr_i32 s65, s40, 31
	v_or_b32_e32 v151, s7, v136
	v_add3_u32 v140, v161, v155, v157
	v_mov_b32_e32 v141, v137
	v_add3_u32 v142, v162, v155, v157
	v_mov_b32_e32 v143, v137
	v_mov_b64_e32 v[144:145], 0xc0
	v_mov_b64_e32 v[146:147], 0xbf
	s_mov_b32 s66, 0x2aaaaaab
	v_add_u32_e32 v180, s67, v149
	v_add_u32_e32 v181, s68, v149
	s_movk_i32 s69, 0x80
	v_mbcnt_hi_u32_b32 v183, -1, v0
	s_mov_b32 s28, 0x3b000000
	s_mov_b32 s70, 0x800000
	s_movk_i32 s71, 0xff40
	s_movk_i32 s72, 0x7f
	s_movk_i32 s73, 0x180
	v_mov_b32_e32 v148, 0x358637bd
	v_mov_b32_e32 v184, 0xfcf
	s_barrier
	s_branch .LBB0_434

; DI void conv_item(LAS unsigned char* lds, int item, const bf16_t* P, const float* cw, const float* cb, const float* lng, const float* lnb, bf16_t* MIX) {
;     ...
;     const int c = tid & 127, tq = tid >> 7;
;     float y[32];
;     {
;         float w[31];
; #pragma unroll
;         for (int k = 0; k < 31; ++k) w[k] = cw[k * 1024 + cbase + c];
;         const float bias = cb[cbase + c];
; #pragma unroll
;         for (int i = 0; i < 32; ++i) y[i] = bias;
;         float uw[62];
; #pragma unroll
;         for (int j = 0; j < 62; ++j) uw[j] = U[(tq * 32 + j) * 128 + c];
; #pragma unroll
;         for (int i = 0; i < 32; ++i)
; #pragma unroll
;             for (int k = 0; k < 31; ++k) y[i] += w[k] * uw[i + k];
.LBB0_517:
	s_or_b64 exec, exec, s[26:27]
	s_lshl_b32 s12, s37, 2
	v_lshrrev_b32_e32 v251, 6, v253
	v_lshlrev_b32_e32 v251, 13, v251
	v_lshl_add_u32 v251, v252, 3, v251
	s_waitcnt lgkmcnt(0)
	s_barrier
	ds_read_b64 v[222:223], v251
	ds_read_b64 v[224:225], v251 offset:512
	ds_read_b64 v[226:227], v251 offset:1024
	ds_read_b64 v[228:229], v251 offset:1536
	ds_read_b64 v[230:231], v251 offset:2048
	ds_read_b64 v[232:233], v251 offset:2560
	ds_read_b64 v[234:235], v251 offset:3072
	ds_read_b64 v[236:237], v251 offset:3584
	ds_read_b64 v[238:239], v251 offset:4096
	ds_read_b64 v[240:241], v251 offset:4608
	ds_read_b64 v[242:243], v251 offset:5120
	ds_read_b64 v[244:245], v251 offset:5632
	ds_read_b64 v[246:247], v251 offset:6144
	ds_read_b64 v[248:249], v251 offset:6656
	ds_read_b64 v[8:9], v251 offset:7168
	ds_read_b64 v[10:11], v251 offset:7680
	ds_read_b64 v[12:13], v251 offset:8192
	ds_read_b64 v[14:15], v251 offset:8704
	ds_read_b64 v[16:17], v251 offset:9216
	ds_read_b64 v[18:19], v251 offset:9728
	ds_read_b64 v[20:21], v251 offset:10240
	ds_read_b64 v[22:23], v251 offset:10752
	ds_read_b64 v[28:29], v251 offset:11264
	ds_read_b64 v[30:31], v251 offset:11776
	ds_read_b64 v[32:33], v251 offset:12288
	ds_read_b64 v[34:35], v251 offset:12800
	ds_read_b64 v[36:37], v251 offset:13312
	ds_read_b64 v[38:39], v251 offset:13824
	ds_read_b64 v[50:51], v251 offset:14336
	ds_read_b64 v[52:53], v251 offset:14848
	ds_read_b64 v[54:55], v251 offset:15360
	ds_read_b64 v[56:57], v251 offset:15872
	ds_read_b64 v[58:59], v251 offset:16384
	ds_read_b64 v[60:61], v251 offset:16896
	ds_read_b64 v[62:63], v251 offset:17408
	ds_read_b64 v[64:65], v251 offset:17920
	ds_read_b64 v[66:67], v251 offset:18432
	ds_read_b64 v[92:93], v251 offset:18944
	ds_read_b64 v[94:95], v251 offset:19456
	ds_read_b64 v[96:97], v251 offset:19968
	ds_read_b64 v[98:99], v251 offset:20480
	ds_read_b64 v[100:101], v251 offset:20992
	ds_read_b64 v[102:103], v251 offset:21504
	ds_read_b64 v[104:105], v251 offset:22016
	ds_read_b64 v[106:107], v251 offset:22528
	ds_read_b64 v[108:109], v251 offset:23040
	s_waitcnt vmcnt(0) lgkmcnt(0)
	s_barrier
	v_pk_fma_f32 v[190:191], v[126:127], v[222:223], v[188:189]
	v_pk_fma_f32 v[190:191], v[128:129], v[224:225], v[190:191]
	v_pk_fma_f32 v[192:193], v[126:127], v[224:225], v[188:189]
	v_pk_fma_f32 v[190:191], v[130:131], v[226:227], v[190:191]
	v_pk_fma_f32 v[192:193], v[128:129], v[226:227], v[192:193]
	v_pk_fma_f32 v[194:195], v[126:127], v[226:227], v[188:189]
	v_pk_fma_f32 v[190:191], v[132:133], v[228:229], v[190:191]
	v_pk_fma_f32 v[192:193], v[130:131], v[228:229], v[192:193]
	v_pk_fma_f32 v[194:195], v[128:129], v[228:229], v[194:195]
	v_pk_fma_f32 v[196:197], v[126:127], v[228:229], v[188:189]
	v_pk_fma_f32 v[190:191], v[134:135], v[230:231], v[190:191]
	v_pk_fma_f32 v[192:193], v[132:133], v[230:231], v[192:193]
	v_pk_fma_f32 v[194:195], v[130:131], v[230:231], v[194:195]
	v_pk_fma_f32 v[196:197], v[128:129], v[230:231], v[196:197]
	v_pk_fma_f32 v[198:199], v[126:127], v[230:231], v[188:189]
	v_pk_fma_f32 v[190:191], v[136:137], v[232:233], v[190:191]
	v_pk_fma_f32 v[192:193], v[134:135], v[232:233], v[192:193]
	v_pk_fma_f32 v[194:195], v[132:133], v[232:233], v[194:195]
	v_pk_fma_f32 v[196:197], v[130:131], v[232:233], v[196:197]
	v_pk_fma_f32 v[198:199], v[128:129], v[232:233], v[198:199]
	v_pk_fma_f32 v[200:201], v[126:127], v[232:233], v[188:189]
	v_pk_fma_f32 v[190:191], v[138:139], v[234:235], v[190:191]
	v_pk_fma_f32 v[192:193], v[136:137], v[234:235], v[192:193]
	v_pk_fma_f32 v[194:195], v[134:135], v[234:235], v[194:195]
	v_pk_fma_f32 v[196:197], v[132:133], v[234:235], v[196:197]
	v_pk_fma_f32 v[198:199], v[130:131], v[234:235], v[198:199]
	v_pk_fma_f32 v[200:201], v[128:129], v[234:235], v[200:201]
	v_pk_fma_f32 v[202:203], v[126:127], v[234:235], v[188:189]
	v_pk_fma_f32 v[190:191], v[140:141], v[236:237], v[190:191]
	v_pk_fma_f32 v[192:193], v[138:139], v[236:237], v[192:193]
	v_pk_fma_f32 v[194:195], v[136:137], v[236:237], v[194:195]
	v_pk_fma_f32 v[196:197], v[134:135], v[236:237], v[196:197]
	v_pk_fma_f32 v[198:199], v[132:133], v[236:237], v[198:199]
	v_pk_fma_f32 v[200:201], v[130:131], v[236:237], v[200:201]
	v_pk_fma_f32 v[202:203], v[128:129], v[236:237], v[202:203]
	v_pk_fma_f32 v[204:205], v[126:127], v[236:237], v[188:189]
	v_pk_fma_f32 v[190:191], v[142:143], v[238:239], v[190:191]
	v_pk_fma_f32 v[192:193], v[140:141], v[238:239], v[192:193]
	v_pk_fma_f32 v[194:195], v[138:139], v[238:239], v[194:195]
	v_pk_fma_f32 v[196:197], v[136:137], v[238:239], v[196:197]
	v_pk_fma_f32 v[198:199], v[134:135], v[238:239], v[198:199]
	v_pk_fma_f32 v[200:201], v[132:133], v[238:239], v[200:201]
	v_pk_fma_f32 v[202:203], v[130:131], v[238:239], v[202:203]
	v_pk_fma_f32 v[204:205], v[128:129], v[238:239], v[204:205]
	v_pk_fma_f32 v[206:207], v[126:127], v[238:239], v[188:189]
	v_pk_fma_f32 v[190:191], v[144:145], v[240:241], v[190:191]
	v_pk_fma_f32 v[192:193], v[142:143], v[240:241], v[192:193]
	v_pk_fma_f32 v[194:195], v[140:141], v[240:241], v[194:195]
	v_pk_fma_f32 v[196:197], v[138:139], v[240:241], v[196:197]
	v_pk_fma_f32 v[198:199], v[136:137], v[240:241], v[198:199]
	v_pk_fma_f32 v[200:201], v[134:135], v[240:241], v[200:201]
	v_pk_fma_f32 v[202:203], v[132:133], v[240:241], v[202:203]
	v_pk_fma_f32 v[204:205], v[130:131], v[240:241], v[204:205]
	v_pk_fma_f32 v[206:207], v[128:129], v[240:241], v[206:207]
	v_pk_fma_f32 v[208:209], v[126:127], v[240:241], v[188:189]
	v_pk_fma_f32 v[190:191], v[146:147], v[242:243], v[190:191]
	v_pk_fma_f32 v[192:193], v[144:145], v[242:243], v[192:193]
; DI void conv_item(LAS unsigned char* lds, int item, const bf16_t* P, const float* cw, const float* cb, const float* lng, const float* lnb, bf16_t* MIX) {
;     ...
;         for (int i = 0; i < 32; ++i)
; #pragma unroll
;             for (int k = 0; k < 31; ++k) y[i] += w[k] * uw[i + k];
	v_pk_fma_f32 v[194:195], v[142:143], v[242:243], v[194:195]
	v_pk_fma_f32 v[196:197], v[140:141], v[242:243], v[196:197]
	v_pk_fma_f32 v[198:199], v[138:139], v[242:243], v[198:199]
	v_pk_fma_f32 v[200:201], v[136:137], v[242:243], v[200:201]
	v_pk_fma_f32 v[202:203], v[134:135], v[242:243], v[202:203]
	v_pk_fma_f32 v[204:205], v[132:133], v[242:243], v[204:205]
	v_pk_fma_f32 v[206:207], v[130:131], v[242:243], v[206:207]
	v_pk_fma_f32 v[208:209], v[128:129], v[242:243], v[208:209]
	v_pk_fma_f32 v[210:211], v[126:127], v[242:243], v[188:189]
	v_pk_fma_f32 v[190:191], v[148:149], v[244:245], v[190:191]
	v_pk_fma_f32 v[192:193], v[146:147], v[244:245], v[192:193]
	v_pk_fma_f32 v[194:195], v[144:145], v[244:245], v[194:195]
	v_pk_fma_f32 v[196:197], v[142:143], v[244:245], v[196:197]
	v_pk_fma_f32 v[198:199], v[140:141], v[244:245], v[198:199]
	v_pk_fma_f32 v[200:201], v[138:139], v[244:245], v[200:201]
	v_pk_fma_f32 v[202:203], v[136:137], v[244:245], v[202:203]
	v_pk_fma_f32 v[204:205], v[134:135], v[244:245], v[204:205]
	v_pk_fma_f32 v[206:207], v[132:133], v[244:245], v[206:207]
	v_pk_fma_f32 v[208:209], v[130:131], v[244:245], v[208:209]
	v_pk_fma_f32 v[210:211], v[128:129], v[244:245], v[210:211]
	v_pk_fma_f32 v[212:213], v[126:127], v[244:245], v[188:189]
	v_pk_fma_f32 v[190:191], v[150:151], v[246:247], v[190:191]
	v_pk_fma_f32 v[192:193], v[148:149], v[246:247], v[192:193]
	v_pk_fma_f32 v[194:195], v[146:147], v[246:247], v[194:195]
	v_pk_fma_f32 v[196:197], v[144:145], v[246:247], v[196:197]
	v_pk_fma_f32 v[198:199], v[142:143], v[246:247], v[198:199]
	v_pk_fma_f32 v[200:201], v[140:141], v[246:247], v[200:201]
	v_pk_fma_f32 v[202:203], v[138:139], v[246:247], v[202:203]
	v_pk_fma_f32 v[204:205], v[136:137], v[246:247], v[204:205]
	v_pk_fma_f32 v[206:207], v[134:135], v[246:247], v[206:207]
	v_pk_fma_f32 v[208:209], v[132:133], v[246:247], v[208:209]
	v_pk_fma_f32 v[210:211], v[130:131], v[246:247], v[210:211]
	v_pk_fma_f32 v[212:213], v[128:129], v[246:247], v[212:213]
	v_pk_fma_f32 v[214:215], v[126:127], v[246:247], v[188:189]
	v_pk_fma_f32 v[190:191], v[152:153], v[248:249], v[190:191]
	v_pk_fma_f32 v[192:193], v[150:151], v[248:249], v[192:193]
	v_pk_fma_f32 v[194:195], v[148:149], v[248:249], v[194:195]
	v_pk_fma_f32 v[196:197], v[146:147], v[248:249], v[196:197]
	v_pk_fma_f32 v[198:199], v[144:145], v[248:249], v[198:199]
	v_pk_fma_f32 v[200:201], v[142:143], v[248:249], v[200:201]
	v_pk_fma_f32 v[202:203], v[140:141], v[248:249], v[202:203]
	v_pk_fma_f32 v[204:205], v[138:139], v[248:249], v[204:205]
	v_pk_fma_f32 v[206:207], v[136:137], v[248:249], v[206:207]
	v_pk_fma_f32 v[208:209], v[134:135], v[248:249], v[208:209]
	v_pk_fma_f32 v[210:211], v[132:133], v[248:249], v[210:211]
	v_pk_fma_f32 v[212:213], v[130:131], v[248:249], v[212:213]
	v_pk_fma_f32 v[214:215], v[128:129], v[248:249], v[214:215]
	v_pk_fma_f32 v[216:217], v[126:127], v[248:249], v[188:189]
	v_pk_fma_f32 v[190:191], v[154:155], v[8:9], v[190:191]
	v_pk_fma_f32 v[192:193], v[152:153], v[8:9], v[192:193]
	v_pk_fma_f32 v[194:195], v[150:151], v[8:9], v[194:195]
	v_pk_fma_f32 v[196:197], v[148:149], v[8:9], v[196:197]
	v_pk_fma_f32 v[198:199], v[146:147], v[8:9], v[198:199]
	v_pk_fma_f32 v[200:201], v[144:145], v[8:9], v[200:201]
	v_pk_fma_f32 v[202:203], v[142:143], v[8:9], v[202:203]
	v_pk_fma_f32 v[204:205], v[140:141], v[8:9], v[204:205]
	v_pk_fma_f32 v[206:207], v[138:139], v[8:9], v[206:207]
	v_pk_fma_f32 v[208:209], v[136:137], v[8:9], v[208:209]
	v_pk_fma_f32 v[210:211], v[134:135], v[8:9], v[210:211]
	v_pk_fma_f32 v[212:213], v[132:133], v[8:9], v[212:213]
	v_pk_fma_f32 v[214:215], v[130:131], v[8:9], v[214:215]
	v_pk_fma_f32 v[216:217], v[128:129], v[8:9], v[216:217]
	v_pk_fma_f32 v[218:219], v[126:127], v[8:9], v[188:189]
	v_pk_fma_f32 v[190:191], v[156:157], v[10:11], v[190:191]
	v_pk_fma_f32 v[192:193], v[154:155], v[10:11], v[192:193]
	v_pk_fma_f32 v[194:195], v[152:153], v[10:11], v[194:195]
	v_pk_fma_f32 v[196:197], v[150:151], v[10:11], v[196:197]
	v_pk_fma_f32 v[198:199], v[148:149], v[10:11], v[198:199]
	v_pk_fma_f32 v[200:201], v[146:147], v[10:11], v[200:201]
	v_pk_fma_f32 v[202:203], v[144:145], v[10:11], v[202:203]
	v_pk_fma_f32 v[204:205], v[142:143], v[10:11], v[204:205]
	v_pk_fma_f32 v[206:207], v[140:141], v[10:11], v[206:207]
	v_pk_fma_f32 v[208:209], v[138:139], v[10:11], v[208:209]
	v_pk_fma_f32 v[210:211], v[136:137], v[10:11], v[210:211]
	v_pk_fma_f32 v[212:213], v[134:135], v[10:11], v[212:213]
	v_pk_fma_f32 v[214:215], v[132:133], v[10:11], v[214:215]
	v_pk_fma_f32 v[216:217], v[130:131], v[10:11], v[216:217]
	v_pk_fma_f32 v[218:219], v[128:129], v[10:11], v[218:219]
	v_pk_fma_f32 v[220:221], v[126:127], v[10:11], v[188:189]
	v_pk_fma_f32 v[190:191], v[158:159], v[12:13], v[190:191]
	v_pk_fma_f32 v[192:193], v[156:157], v[12:13], v[192:193]
	v_pk_fma_f32 v[194:195], v[154:155], v[12:13], v[194:195]
	v_pk_fma_f32 v[196:197], v[152:153], v[12:13], v[196:197]
	v_pk_fma_f32 v[198:199], v[150:151], v[12:13], v[198:199]
	v_pk_fma_f32 v[200:201], v[148:149], v[12:13], v[200:201]
	v_pk_fma_f32 v[202:203], v[146:147], v[12:13], v[202:203]
	v_pk_fma_f32 v[204:205], v[144:145], v[12:13], v[204:205]
	v_pk_fma_f32 v[206:207], v[142:143], v[12:13], v[206:207]
	v_pk_fma_f32 v[208:209], v[140:141], v[12:13], v[208:209]
	v_pk_fma_f32 v[210:211], v[138:139], v[12:13], v[210:211]
	v_pk_fma_f32 v[212:213], v[136:137], v[12:13], v[212:213]
	v_pk_fma_f32 v[214:215], v[134:135], v[12:13], v[214:215]
	v_pk_fma_f32 v[216:217], v[132:133], v[12:13], v[216:217]
	v_pk_fma_f32 v[218:219], v[130:131], v[12:13], v[218:219]
; DI void conv_item(LAS unsigned char* lds, int item, const bf16_t* P, const float* cw, const float* cb, const float* lng, const float* lnb, bf16_t* MIX) {
;     ...
;         for (int i = 0; i < 32; ++i)
; #pragma unroll
;             for (int k = 0; k < 31; ++k) y[i] += w[k] * uw[i + k];
	v_pk_fma_f32 v[220:221], v[128:129], v[12:13], v[220:221]
	v_pk_fma_f32 v[190:191], v[160:161], v[14:15], v[190:191]
	v_pk_fma_f32 v[192:193], v[158:159], v[14:15], v[192:193]
	v_pk_fma_f32 v[194:195], v[156:157], v[14:15], v[194:195]
	v_pk_fma_f32 v[196:197], v[154:155], v[14:15], v[196:197]
	v_pk_fma_f32 v[198:199], v[152:153], v[14:15], v[198:199]
	v_pk_fma_f32 v[200:201], v[150:151], v[14:15], v[200:201]
	v_pk_fma_f32 v[202:203], v[148:149], v[14:15], v[202:203]
	v_pk_fma_f32 v[204:205], v[146:147], v[14:15], v[204:205]
	v_pk_fma_f32 v[206:207], v[144:145], v[14:15], v[206:207]
	v_pk_fma_f32 v[208:209], v[142:143], v[14:15], v[208:209]
	v_pk_fma_f32 v[210:211], v[140:141], v[14:15], v[210:211]
	v_pk_fma_f32 v[212:213], v[138:139], v[14:15], v[212:213]
	v_pk_fma_f32 v[214:215], v[136:137], v[14:15], v[214:215]
	v_pk_fma_f32 v[216:217], v[134:135], v[14:15], v[216:217]
	v_pk_fma_f32 v[218:219], v[132:133], v[14:15], v[218:219]
	v_pk_fma_f32 v[220:221], v[130:131], v[14:15], v[220:221]
	v_pk_fma_f32 v[190:191], v[162:163], v[16:17], v[190:191]
	v_pk_fma_f32 v[192:193], v[160:161], v[16:17], v[192:193]
	v_pk_fma_f32 v[194:195], v[158:159], v[16:17], v[194:195]
	v_pk_fma_f32 v[196:197], v[156:157], v[16:17], v[196:197]
	v_pk_fma_f32 v[198:199], v[154:155], v[16:17], v[198:199]
	v_pk_fma_f32 v[200:201], v[152:153], v[16:17], v[200:201]
	v_pk_fma_f32 v[202:203], v[150:151], v[16:17], v[202:203]
	v_pk_fma_f32 v[204:205], v[148:149], v[16:17], v[204:205]
	v_pk_fma_f32 v[206:207], v[146:147], v[16:17], v[206:207]
	v_pk_fma_f32 v[208:209], v[144:145], v[16:17], v[208:209]
	v_pk_fma_f32 v[210:211], v[142:143], v[16:17], v[210:211]
	v_pk_fma_f32 v[212:213], v[140:141], v[16:17], v[212:213]
	v_pk_fma_f32 v[214:215], v[138:139], v[16:17], v[214:215]
	v_pk_fma_f32 v[216:217], v[136:137], v[16:17], v[216:217]
	v_pk_fma_f32 v[218:219], v[134:135], v[16:17], v[218:219]
	v_pk_fma_f32 v[220:221], v[132:133], v[16:17], v[220:221]
	v_pk_fma_f32 v[190:191], v[164:165], v[18:19], v[190:191]
	v_pk_fma_f32 v[192:193], v[162:163], v[18:19], v[192:193]
	v_pk_fma_f32 v[194:195], v[160:161], v[18:19], v[194:195]
	v_pk_fma_f32 v[196:197], v[158:159], v[18:19], v[196:197]
	v_pk_fma_f32 v[198:199], v[156:157], v[18:19], v[198:199]
	v_pk_fma_f32 v[200:201], v[154:155], v[18:19], v[200:201]
	v_pk_fma_f32 v[202:203], v[152:153], v[18:19], v[202:203]
	v_pk_fma_f32 v[204:205], v[150:151], v[18:19], v[204:205]
	v_pk_fma_f32 v[206:207], v[148:149], v[18:19], v[206:207]
	v_pk_fma_f32 v[208:209], v[146:147], v[18:19], v[208:209]
	v_pk_fma_f32 v[210:211], v[144:145], v[18:19], v[210:211]
	v_pk_fma_f32 v[212:213], v[142:143], v[18:19], v[212:213]
	v_pk_fma_f32 v[214:215], v[140:141], v[18:19], v[214:215]
	v_pk_fma_f32 v[216:217], v[138:139], v[18:19], v[216:217]
	v_pk_fma_f32 v[218:219], v[136:137], v[18:19], v[218:219]
	v_pk_fma_f32 v[220:221], v[134:135], v[18:19], v[220:221]
	v_pk_fma_f32 v[190:191], v[166:167], v[20:21], v[190:191]
	v_pk_fma_f32 v[192:193], v[164:165], v[20:21], v[192:193]
	v_pk_fma_f32 v[194:195], v[162:163], v[20:21], v[194:195]
	v_pk_fma_f32 v[196:197], v[160:161], v[20:21], v[196:197]
	v_pk_fma_f32 v[198:199], v[158:159], v[20:21], v[198:199]
	v_pk_fma_f32 v[200:201], v[156:157], v[20:21], v[200:201]
	v_pk_fma_f32 v[202:203], v[154:155], v[20:21], v[202:203]
	v_pk_fma_f32 v[204:205], v[152:153], v[20:21], v[204:205]
	v_pk_fma_f32 v[206:207], v[150:151], v[20:21], v[206:207]
	v_pk_fma_f32 v[208:209], v[148:149], v[20:21], v[208:209]
	v_pk_fma_f32 v[210:211], v[146:147], v[20:21], v[210:211]
	v_pk_fma_f32 v[212:213], v[144:145], v[20:21], v[212:213]
	v_pk_fma_f32 v[214:215], v[142:143], v[20:21], v[214:215]
	v_pk_fma_f32 v[216:217], v[140:141], v[20:21], v[216:217]
	v_pk_fma_f32 v[218:219], v[138:139], v[20:21], v[218:219]
	v_pk_fma_f32 v[220:221], v[136:137], v[20:21], v[220:221]
	v_pk_fma_f32 v[190:191], v[168:169], v[22:23], v[190:191]
	v_pk_fma_f32 v[192:193], v[166:167], v[22:23], v[192:193]
	v_pk_fma_f32 v[194:195], v[164:165], v[22:23], v[194:195]
	v_pk_fma_f32 v[196:197], v[162:163], v[22:23], v[196:197]
	v_pk_fma_f32 v[198:199], v[160:161], v[22:23], v[198:199]
	v_pk_fma_f32 v[200:201], v[158:159], v[22:23], v[200:201]
	v_pk_fma_f32 v[202:203], v[156:157], v[22:23], v[202:203]
	v_pk_fma_f32 v[204:205], v[154:155], v[22:23], v[204:205]
	v_pk_fma_f32 v[206:207], v[152:153], v[22:23], v[206:207]
	v_pk_fma_f32 v[208:209], v[150:151], v[22:23], v[208:209]
	v_pk_fma_f32 v[210:211], v[148:149], v[22:23], v[210:211]
	v_pk_fma_f32 v[212:213], v[146:147], v[22:23], v[212:213]
	v_pk_fma_f32 v[214:215], v[144:145], v[22:23], v[214:215]
	v_pk_fma_f32 v[216:217], v[142:143], v[22:23], v[216:217]
	v_pk_fma_f32 v[218:219], v[140:141], v[22:23], v[218:219]
	v_pk_fma_f32 v[220:221], v[138:139], v[22:23], v[220:221]
	v_pk_fma_f32 v[190:191], v[170:171], v[28:29], v[190:191]
	v_pk_fma_f32 v[192:193], v[168:169], v[28:29], v[192:193]
	v_pk_fma_f32 v[194:195], v[166:167], v[28:29], v[194:195]
	v_pk_fma_f32 v[196:197], v[164:165], v[28:29], v[196:197]
	v_pk_fma_f32 v[198:199], v[162:163], v[28:29], v[198:199]
	v_pk_fma_f32 v[200:201], v[160:161], v[28:29], v[200:201]
	v_pk_fma_f32 v[202:203], v[158:159], v[28:29], v[202:203]
	v_pk_fma_f32 v[204:205], v[156:157], v[28:29], v[204:205]
	v_pk_fma_f32 v[206:207], v[154:155], v[28:29], v[206:207]
	v_pk_fma_f32 v[208:209], v[152:153], v[28:29], v[208:209]
	v_pk_fma_f32 v[210:211], v[150:151], v[28:29], v[210:211]
	v_pk_fma_f32 v[212:213], v[148:149], v[28:29], v[212:213]
	v_pk_fma_f32 v[214:215], v[146:147], v[28:29], v[214:215]
	v_pk_fma_f32 v[216:217], v[144:145], v[28:29], v[216:217]
	v_pk_fma_f32 v[218:219], v[142:143], v[28:29], v[218:219]
; DI void conv_item(LAS unsigned char* lds, int item, const bf16_t* P, const float* cw, const float* cb, const float* lng, const float* lnb, bf16_t* MIX) {
;     ...
;         for (int i = 0; i < 32; ++i)
; #pragma unroll
;             for (int k = 0; k < 31; ++k) y[i] += w[k] * uw[i + k];
	v_pk_fma_f32 v[220:221], v[140:141], v[28:29], v[220:221]
	v_pk_fma_f32 v[190:191], v[172:173], v[30:31], v[190:191]
	v_pk_fma_f32 v[192:193], v[170:171], v[30:31], v[192:193]
	v_pk_fma_f32 v[194:195], v[168:169], v[30:31], v[194:195]
	v_pk_fma_f32 v[196:197], v[166:167], v[30:31], v[196:197]
	v_pk_fma_f32 v[198:199], v[164:165], v[30:31], v[198:199]
	v_pk_fma_f32 v[200:201], v[162:163], v[30:31], v[200:201]
	v_pk_fma_f32 v[202:203], v[160:161], v[30:31], v[202:203]
	v_pk_fma_f32 v[204:205], v[158:159], v[30:31], v[204:205]
	v_pk_fma_f32 v[206:207], v[156:157], v[30:31], v[206:207]
	v_pk_fma_f32 v[208:209], v[154:155], v[30:31], v[208:209]
	v_pk_fma_f32 v[210:211], v[152:153], v[30:31], v[210:211]
	v_pk_fma_f32 v[212:213], v[150:151], v[30:31], v[212:213]
	v_pk_fma_f32 v[214:215], v[148:149], v[30:31], v[214:215]
	v_pk_fma_f32 v[216:217], v[146:147], v[30:31], v[216:217]
	v_pk_fma_f32 v[218:219], v[144:145], v[30:31], v[218:219]
	v_pk_fma_f32 v[220:221], v[142:143], v[30:31], v[220:221]
	v_pk_fma_f32 v[190:191], v[174:175], v[32:33], v[190:191]
	v_pk_fma_f32 v[192:193], v[172:173], v[32:33], v[192:193]
	v_pk_fma_f32 v[194:195], v[170:171], v[32:33], v[194:195]
	v_pk_fma_f32 v[196:197], v[168:169], v[32:33], v[196:197]
	v_pk_fma_f32 v[198:199], v[166:167], v[32:33], v[198:199]
	v_pk_fma_f32 v[200:201], v[164:165], v[32:33], v[200:201]
	v_pk_fma_f32 v[202:203], v[162:163], v[32:33], v[202:203]
	v_pk_fma_f32 v[204:205], v[160:161], v[32:33], v[204:205]
	v_pk_fma_f32 v[206:207], v[158:159], v[32:33], v[206:207]
	v_pk_fma_f32 v[208:209], v[156:157], v[32:33], v[208:209]
	v_pk_fma_f32 v[210:211], v[154:155], v[32:33], v[210:211]
	v_pk_fma_f32 v[212:213], v[152:153], v[32:33], v[212:213]
	v_pk_fma_f32 v[214:215], v[150:151], v[32:33], v[214:215]
	v_pk_fma_f32 v[216:217], v[148:149], v[32:33], v[216:217]
	v_pk_fma_f32 v[218:219], v[146:147], v[32:33], v[218:219]
	v_pk_fma_f32 v[220:221], v[144:145], v[32:33], v[220:221]
	v_pk_fma_f32 v[190:191], v[176:177], v[34:35], v[190:191]
	v_pk_fma_f32 v[192:193], v[174:175], v[34:35], v[192:193]
	v_pk_fma_f32 v[194:195], v[172:173], v[34:35], v[194:195]
	v_pk_fma_f32 v[196:197], v[170:171], v[34:35], v[196:197]
	v_pk_fma_f32 v[198:199], v[168:169], v[34:35], v[198:199]
	v_pk_fma_f32 v[200:201], v[166:167], v[34:35], v[200:201]
	v_pk_fma_f32 v[202:203], v[164:165], v[34:35], v[202:203]
	v_pk_fma_f32 v[204:205], v[162:163], v[34:35], v[204:205]
	v_pk_fma_f32 v[206:207], v[160:161], v[34:35], v[206:207]
	v_pk_fma_f32 v[208:209], v[158:159], v[34:35], v[208:209]
	v_pk_fma_f32 v[210:211], v[156:157], v[34:35], v[210:211]
	v_pk_fma_f32 v[212:213], v[154:155], v[34:35], v[212:213]
	v_pk_fma_f32 v[214:215], v[152:153], v[34:35], v[214:215]
	v_pk_fma_f32 v[216:217], v[150:151], v[34:35], v[216:217]
	v_pk_fma_f32 v[218:219], v[148:149], v[34:35], v[218:219]
	v_pk_fma_f32 v[220:221], v[146:147], v[34:35], v[220:221]
	v_pk_fma_f32 v[190:191], v[178:179], v[36:37], v[190:191]
	v_pk_fma_f32 v[192:193], v[176:177], v[36:37], v[192:193]
	v_pk_fma_f32 v[194:195], v[174:175], v[36:37], v[194:195]
	v_pk_fma_f32 v[196:197], v[172:173], v[36:37], v[196:197]
	v_pk_fma_f32 v[198:199], v[170:171], v[36:37], v[198:199]
	v_pk_fma_f32 v[200:201], v[168:169], v[36:37], v[200:201]
	v_pk_fma_f32 v[202:203], v[166:167], v[36:37], v[202:203]
	v_pk_fma_f32 v[204:205], v[164:165], v[36:37], v[204:205]
	v_pk_fma_f32 v[206:207], v[162:163], v[36:37], v[206:207]
	v_pk_fma_f32 v[208:209], v[160:161], v[36:37], v[208:209]
	v_pk_fma_f32 v[210:211], v[158:159], v[36:37], v[210:211]
	v_pk_fma_f32 v[212:213], v[156:157], v[36:37], v[212:213]
	v_pk_fma_f32 v[214:215], v[154:155], v[36:37], v[214:215]
	v_pk_fma_f32 v[216:217], v[152:153], v[36:37], v[216:217]
	v_pk_fma_f32 v[218:219], v[150:151], v[36:37], v[218:219]
	v_pk_fma_f32 v[220:221], v[148:149], v[36:37], v[220:221]
	v_pk_fma_f32 v[190:191], v[180:181], v[38:39], v[190:191]
	v_pk_fma_f32 v[192:193], v[178:179], v[38:39], v[192:193]
	v_pk_fma_f32 v[194:195], v[176:177], v[38:39], v[194:195]
	v_pk_fma_f32 v[196:197], v[174:175], v[38:39], v[196:197]
	v_pk_fma_f32 v[198:199], v[172:173], v[38:39], v[198:199]
	v_pk_fma_f32 v[200:201], v[170:171], v[38:39], v[200:201]
	v_pk_fma_f32 v[202:203], v[168:169], v[38:39], v[202:203]
	v_pk_fma_f32 v[204:205], v[166:167], v[38:39], v[204:205]
	v_pk_fma_f32 v[206:207], v[164:165], v[38:39], v[206:207]
	v_pk_fma_f32 v[208:209], v[162:163], v[38:39], v[208:209]
	v_pk_fma_f32 v[210:211], v[160:161], v[38:39], v[210:211]
	v_pk_fma_f32 v[212:213], v[158:159], v[38:39], v[212:213]
	v_pk_fma_f32 v[214:215], v[156:157], v[38:39], v[214:215]
	v_pk_fma_f32 v[216:217], v[154:155], v[38:39], v[216:217]
	v_pk_fma_f32 v[218:219], v[152:153], v[38:39], v[218:219]
	v_pk_fma_f32 v[220:221], v[150:151], v[38:39], v[220:221]
	v_pk_fma_f32 v[190:191], v[182:183], v[50:51], v[190:191]
	v_pk_fma_f32 v[192:193], v[180:181], v[50:51], v[192:193]
	v_pk_fma_f32 v[194:195], v[178:179], v[50:51], v[194:195]
	v_pk_fma_f32 v[196:197], v[176:177], v[50:51], v[196:197]
	v_pk_fma_f32 v[198:199], v[174:175], v[50:51], v[198:199]
	v_pk_fma_f32 v[200:201], v[172:173], v[50:51], v[200:201]
	v_pk_fma_f32 v[202:203], v[170:171], v[50:51], v[202:203]
	v_pk_fma_f32 v[204:205], v[168:169], v[50:51], v[204:205]
	v_pk_fma_f32 v[206:207], v[166:167], v[50:51], v[206:207]
	v_pk_fma_f32 v[208:209], v[164:165], v[50:51], v[208:209]
	v_pk_fma_f32 v[210:211], v[162:163], v[50:51], v[210:211]
	v_pk_fma_f32 v[212:213], v[160:161], v[50:51], v[212:213]
	v_pk_fma_f32 v[214:215], v[158:159], v[50:51], v[214:215]
	v_pk_fma_f32 v[216:217], v[156:157], v[50:51], v[216:217]
	v_pk_fma_f32 v[218:219], v[154:155], v[50:51], v[218:219]
; DI void conv_item(LAS unsigned char* lds, int item, const bf16_t* P, const float* cw, const float* cb, const float* lng, const float* lnb, bf16_t* MIX) {
;     ...
;         for (int i = 0; i < 32; ++i)
; #pragma unroll
;             for (int k = 0; k < 31; ++k) y[i] += w[k] * uw[i + k];
;     ...
;             const int t = wid * 16 + it * 4 + ts;
;             const size_t row = (size_t)(tt0 + t);
;             const u32x2 za = *(const u32x2*)(P + row * LDP + 2048 + cbase + ca), zb = *(const u32x2*)(P + row * LDP + 2048 + cbase + cb2);
	v_pk_fma_f32 v[220:221], v[152:153], v[50:51], v[220:221]
	v_pk_fma_f32 v[190:191], v[184:185], v[52:53], v[190:191]
	v_pk_fma_f32 v[192:193], v[182:183], v[52:53], v[192:193]
	v_pk_fma_f32 v[194:195], v[180:181], v[52:53], v[194:195]
	v_pk_fma_f32 v[196:197], v[178:179], v[52:53], v[196:197]
	v_pk_fma_f32 v[198:199], v[176:177], v[52:53], v[198:199]
	v_pk_fma_f32 v[200:201], v[174:175], v[52:53], v[200:201]
	v_pk_fma_f32 v[202:203], v[172:173], v[52:53], v[202:203]
	v_pk_fma_f32 v[204:205], v[170:171], v[52:53], v[204:205]
	v_pk_fma_f32 v[206:207], v[168:169], v[52:53], v[206:207]
	v_pk_fma_f32 v[208:209], v[166:167], v[52:53], v[208:209]
	v_pk_fma_f32 v[210:211], v[164:165], v[52:53], v[210:211]
	v_pk_fma_f32 v[212:213], v[162:163], v[52:53], v[212:213]
	v_pk_fma_f32 v[214:215], v[160:161], v[52:53], v[214:215]
	v_pk_fma_f32 v[216:217], v[158:159], v[52:53], v[216:217]
	v_pk_fma_f32 v[218:219], v[156:157], v[52:53], v[218:219]
	v_pk_fma_f32 v[220:221], v[154:155], v[52:53], v[220:221]
	v_pk_fma_f32 v[190:191], v[186:187], v[54:55], v[190:191]
	v_pk_fma_f32 v[192:193], v[184:185], v[54:55], v[192:193]
	v_pk_fma_f32 v[194:195], v[182:183], v[54:55], v[194:195]
	v_pk_fma_f32 v[196:197], v[180:181], v[54:55], v[196:197]
	v_pk_fma_f32 v[198:199], v[178:179], v[54:55], v[198:199]
	v_pk_fma_f32 v[200:201], v[176:177], v[54:55], v[200:201]
	v_pk_fma_f32 v[202:203], v[174:175], v[54:55], v[202:203]
	v_pk_fma_f32 v[204:205], v[172:173], v[54:55], v[204:205]
	v_pk_fma_f32 v[206:207], v[170:171], v[54:55], v[206:207]
	v_pk_fma_f32 v[208:209], v[168:169], v[54:55], v[208:209]
	v_pk_fma_f32 v[210:211], v[166:167], v[54:55], v[210:211]
	v_pk_fma_f32 v[212:213], v[164:165], v[54:55], v[212:213]
	v_pk_fma_f32 v[214:215], v[162:163], v[54:55], v[214:215]
	v_pk_fma_f32 v[216:217], v[160:161], v[54:55], v[216:217]
	v_pk_fma_f32 v[218:219], v[158:159], v[54:55], v[218:219]
	v_pk_fma_f32 v[220:221], v[156:157], v[54:55], v[220:221]
	v_pk_fma_f32 v[192:193], v[186:187], v[56:57], v[192:193]
	v_pk_fma_f32 v[194:195], v[184:185], v[56:57], v[194:195]
	v_pk_fma_f32 v[196:197], v[182:183], v[56:57], v[196:197]
	v_pk_fma_f32 v[198:199], v[180:181], v[56:57], v[198:199]
	v_pk_fma_f32 v[200:201], v[178:179], v[56:57], v[200:201]
	v_pk_fma_f32 v[202:203], v[176:177], v[56:57], v[202:203]
	v_pk_fma_f32 v[204:205], v[174:175], v[56:57], v[204:205]
	v_pk_fma_f32 v[206:207], v[172:173], v[56:57], v[206:207]
	v_pk_fma_f32 v[208:209], v[170:171], v[56:57], v[208:209]
	v_pk_fma_f32 v[210:211], v[168:169], v[56:57], v[210:211]
	v_pk_fma_f32 v[212:213], v[166:167], v[56:57], v[212:213]
	v_pk_fma_f32 v[214:215], v[164:165], v[56:57], v[214:215]
	v_pk_fma_f32 v[216:217], v[162:163], v[56:57], v[216:217]
	v_pk_fma_f32 v[218:219], v[160:161], v[56:57], v[218:219]
	v_pk_fma_f32 v[220:221], v[158:159], v[56:57], v[220:221]
	v_pk_fma_f32 v[194:195], v[186:187], v[58:59], v[194:195]
	v_pk_fma_f32 v[196:197], v[184:185], v[58:59], v[196:197]
	v_pk_fma_f32 v[198:199], v[182:183], v[58:59], v[198:199]
	v_pk_fma_f32 v[200:201], v[180:181], v[58:59], v[200:201]
	v_pk_fma_f32 v[202:203], v[178:179], v[58:59], v[202:203]
	v_pk_fma_f32 v[204:205], v[176:177], v[58:59], v[204:205]
	v_pk_fma_f32 v[206:207], v[174:175], v[58:59], v[206:207]
	v_pk_fma_f32 v[208:209], v[172:173], v[58:59], v[208:209]
	v_pk_fma_f32 v[210:211], v[170:171], v[58:59], v[210:211]
	v_pk_fma_f32 v[212:213], v[168:169], v[58:59], v[212:213]
	v_pk_fma_f32 v[214:215], v[166:167], v[58:59], v[214:215]
	v_pk_fma_f32 v[216:217], v[164:165], v[58:59], v[216:217]
	v_pk_fma_f32 v[218:219], v[162:163], v[58:59], v[218:219]
	v_pk_fma_f32 v[220:221], v[160:161], v[58:59], v[220:221]
	v_pk_fma_f32 v[196:197], v[186:187], v[60:61], v[196:197]
	v_pk_fma_f32 v[198:199], v[184:185], v[60:61], v[198:199]
	v_pk_fma_f32 v[200:201], v[182:183], v[60:61], v[200:201]
	v_pk_fma_f32 v[202:203], v[180:181], v[60:61], v[202:203]
	v_add_u32_e32 v26, s36, v80
	v_pk_fma_f32 v[204:205], v[178:179], v[60:61], v[204:205]
	v_pk_fma_f32 v[206:207], v[176:177], v[60:61], v[206:207]
	v_pk_fma_f32 v[208:209], v[174:175], v[60:61], v[208:209]
	v_pk_fma_f32 v[210:211], v[172:173], v[60:61], v[210:211]
	v_pk_fma_f32 v[212:213], v[170:171], v[60:61], v[212:213]
	v_pk_fma_f32 v[214:215], v[168:169], v[60:61], v[214:215]
	v_pk_fma_f32 v[216:217], v[166:167], v[60:61], v[216:217]
	v_pk_fma_f32 v[218:219], v[164:165], v[60:61], v[218:219]
	v_mov_b64_e32 v[24:25], s[62:63]
	v_pk_fma_f32 v[220:221], v[162:163], v[60:61], v[220:221]
	v_pk_fma_f32 v[198:199], v[186:187], v[62:63], v[198:199]
	v_pk_fma_f32 v[200:201], v[184:185], v[62:63], v[200:201]
	v_pk_fma_f32 v[202:203], v[182:183], v[62:63], v[202:203]
	v_pk_fma_f32 v[204:205], v[180:181], v[62:63], v[204:205]
	v_pk_fma_f32 v[206:207], v[178:179], v[62:63], v[206:207]
	v_pk_fma_f32 v[208:209], v[176:177], v[62:63], v[208:209]
	v_pk_fma_f32 v[210:211], v[174:175], v[62:63], v[210:211]
	v_lshl_add_u64 v[0:1], v[42:43], 0, s[12:13]
	v_pk_fma_f32 v[212:213], v[172:173], v[62:63], v[212:213]
	v_pk_fma_f32 v[214:215], v[170:171], v[62:63], v[214:215]
	v_pk_fma_f32 v[216:217], v[168:169], v[62:63], v[216:217]
	v_pk_fma_f32 v[218:219], v[166:167], v[62:63], v[218:219]
	v_pk_fma_f32 v[220:221], v[164:165], v[62:63], v[220:221]
	v_pk_fma_f32 v[200:201], v[186:187], v[64:65], v[200:201]
	v_pk_fma_f32 v[202:203], v[184:185], v[64:65], v[202:203]
	v_pk_fma_f32 v[204:205], v[182:183], v[64:65], v[204:205]
	v_lshl_add_u64 v[4:5], v[44:45], 0, s[12:13]
	v_pk_fma_f32 v[206:207], v[180:181], v[64:65], v[206:207]
	v_pk_fma_f32 v[208:209], v[178:179], v[64:65], v[208:209]
	v_pk_fma_f32 v[210:211], v[176:177], v[64:65], v[210:211]
; DI void conv_item(LAS unsigned char* lds, int item, const bf16_t* P, const float* cw, const float* cb, const float* lng, const float* lnb, bf16_t* MIX) {
;     ...
;         for (int i = 0; i < 32; ++i)
; #pragma unroll
;             for (int k = 0; k < 31; ++k) y[i] += w[k] * uw[i + k];
;     }
;     __syncthreads();
; #pragma unroll
;     for (int i = 0; i < 32; ++i) U[(tq * 32 + i) * 128 + c] = y[i];
;     __syncthreads();
	v_pk_fma_f32 v[212:213], v[174:175], v[64:65], v[212:213]
	v_pk_fma_f32 v[214:215], v[172:173], v[64:65], v[214:215]
	v_pk_fma_f32 v[216:217], v[170:171], v[64:65], v[216:217]
	v_pk_fma_f32 v[218:219], v[168:169], v[64:65], v[218:219]
	v_pk_fma_f32 v[220:221], v[166:167], v[64:65], v[220:221]
	s_lshl_b32 s12, s37, 1
	v_pk_fma_f32 v[202:203], v[186:187], v[66:67], v[202:203]
	v_pk_fma_f32 v[204:205], v[184:185], v[66:67], v[204:205]
	v_pk_fma_f32 v[206:207], v[182:183], v[66:67], v[206:207]
	v_pk_fma_f32 v[208:209], v[180:181], v[66:67], v[208:209]
	v_pk_fma_f32 v[210:211], v[178:179], v[66:67], v[210:211]
	v_pk_fma_f32 v[212:213], v[176:177], v[66:67], v[212:213]
	v_pk_fma_f32 v[214:215], v[174:175], v[66:67], v[214:215]
	v_pk_fma_f32 v[216:217], v[172:173], v[66:67], v[216:217]
	v_mad_i64_i32 v[2:3], s[26:27], v26, s30, v[24:25]
	v_pk_fma_f32 v[218:219], v[170:171], v[66:67], v[218:219]
	v_pk_fma_f32 v[220:221], v[168:169], v[66:67], v[220:221]
	v_pk_fma_f32 v[204:205], v[186:187], v[92:93], v[204:205]
	v_pk_fma_f32 v[206:207], v[184:185], v[92:93], v[206:207]
	v_pk_fma_f32 v[208:209], v[182:183], v[92:93], v[208:209]
	v_pk_fma_f32 v[210:211], v[180:181], v[92:93], v[210:211]
	v_pk_fma_f32 v[212:213], v[178:179], v[92:93], v[212:213]
	v_pk_fma_f32 v[214:215], v[176:177], v[92:93], v[214:215]
	v_lshl_add_u64 v[2:3], v[2:3], 0, s[12:13]
	v_pk_fma_f32 v[216:217], v[174:175], v[92:93], v[216:217]
	v_pk_fma_f32 v[218:219], v[172:173], v[92:93], v[218:219]
	v_pk_fma_f32 v[220:221], v[170:171], v[92:93], v[220:221]
	v_pk_fma_f32 v[206:207], v[186:187], v[94:95], v[206:207]
	v_pk_fma_f32 v[208:209], v[184:185], v[94:95], v[208:209]
	v_pk_fma_f32 v[210:211], v[182:183], v[94:95], v[210:211]
	v_pk_fma_f32 v[212:213], v[180:181], v[94:95], v[212:213]
	v_pk_fma_f32 v[214:215], v[178:179], v[94:95], v[214:215]
	v_mov_b32_e32 v47, v41
	v_pk_fma_f32 v[216:217], v[176:177], v[94:95], v[216:217]
	v_pk_fma_f32 v[218:219], v[174:175], v[94:95], v[218:219]
	v_pk_fma_f32 v[220:221], v[172:173], v[94:95], v[220:221]
	v_pk_fma_f32 v[208:209], v[186:187], v[96:97], v[208:209]
	v_pk_fma_f32 v[210:211], v[184:185], v[96:97], v[210:211]
	v_pk_fma_f32 v[212:213], v[182:183], v[96:97], v[212:213]
	v_pk_fma_f32 v[214:215], v[180:181], v[96:97], v[214:215]
	v_pk_fma_f32 v[216:217], v[178:179], v[96:97], v[216:217]
	v_lshl_add_u64 v[2:3], v[2:3], 0, v[46:47]
	v_pk_fma_f32 v[218:219], v[176:177], v[96:97], v[218:219]
	v_pk_fma_f32 v[220:221], v[174:175], v[96:97], v[220:221]
	v_pk_fma_f32 v[210:211], v[186:187], v[98:99], v[210:211]
	v_pk_fma_f32 v[212:213], v[184:185], v[98:99], v[212:213]
	v_pk_fma_f32 v[214:215], v[182:183], v[98:99], v[214:215]
	v_pk_fma_f32 v[216:217], v[180:181], v[98:99], v[216:217]
	v_pk_fma_f32 v[218:219], v[178:179], v[98:99], v[218:219]
	v_pk_fma_f32 v[220:221], v[176:177], v[98:99], v[220:221]
	v_add_co_u32_e32 v6, vcc, s31, v2
	v_pk_fma_f32 v[212:213], v[186:187], v[100:101], v[212:213]
	v_pk_fma_f32 v[214:215], v[184:185], v[100:101], v[214:215]
	v_pk_fma_f32 v[216:217], v[182:183], v[100:101], v[216:217]
	v_pk_fma_f32 v[218:219], v[180:181], v[100:101], v[218:219]
	v_pk_fma_f32 v[220:221], v[178:179], v[100:101], v[220:221]
	v_pk_fma_f32 v[214:215], v[186:187], v[102:103], v[214:215]
	v_pk_fma_f32 v[216:217], v[184:185], v[102:103], v[216:217]
	v_pk_fma_f32 v[218:219], v[182:183], v[102:103], v[218:219]
	v_addc_co_u32_e32 v7, vcc, 0, v3, vcc
	v_pk_fma_f32 v[220:221], v[180:181], v[102:103], v[220:221]
	v_pk_fma_f32 v[216:217], v[186:187], v[104:105], v[216:217]
	v_pk_fma_f32 v[218:219], v[184:185], v[104:105], v[218:219]
	v_pk_fma_f32 v[220:221], v[182:183], v[104:105], v[220:221]
	v_pk_fma_f32 v[218:219], v[186:187], v[106:107], v[218:219]
	v_pk_fma_f32 v[220:221], v[184:185], v[106:107], v[220:221]
	v_pk_fma_f32 v[220:221], v[186:187], v[108:109], v[220:221]
	ds_write_b64 v251, v[190:191]
	ds_write_b64 v251, v[192:193] offset:512
	ds_write_b64 v251, v[194:195] offset:1024
	ds_write_b64 v251, v[196:197] offset:1536
	ds_write_b64 v251, v[198:199] offset:2048
	ds_write_b64 v251, v[200:201] offset:2560
	ds_write_b64 v251, v[202:203] offset:3072
	ds_write_b64 v251, v[204:205] offset:3584
	ds_write_b64 v251, v[206:207] offset:4096
	ds_write_b64 v251, v[208:209] offset:4608
	ds_write_b64 v251, v[210:211] offset:5120
	ds_write_b64 v251, v[212:213] offset:5632
	ds_write_b64 v251, v[214:215] offset:6144
	ds_write_b64 v251, v[216:217] offset:6656
	ds_write_b64 v251, v[218:219] offset:7168
	ds_write_b64 v251, v[220:221] offset:7680
	s_waitcnt lgkmcnt(0)
	s_barrier
; #define LAS __attribute__((address_space(3)))
; DI float siluf_(float x) { return x * frcp(1.f + fexp(-x)); }
; DI float dot4(const f32x4 a) { return (a[0] * a[0] + a[1] * a[1]) + (a[2] * a[2] + a[3] * a[3]); }
; DI void conv_item(LAS unsigned char* lds, int item, const bf16_t* P, const float* cw, const float* cb, const float* lng, const float* lnb, bf16_t* MIX) {
;     ...
;         const f32x4 ga = *(const f32x4*)(lng + cbase + ca), gb = *(const f32x4*)(lng + cbase + cb2);
;         const f32x4 ba = *(const f32x4*)(lnb + cbase + ca), bb = *(const f32x4*)(lnb + cbase + cb2);
; #pragma unroll
;         for (int it = 0; it < 4; ++it) {
;             const int t = wid * 16 + it * 4 + ts;
;             const size_t row = (size_t)(tt0 + t);
;             const u32x2 za = *(const u32x2*)(P + row * LDP + 2048 + cbase + ca), zb = *(const u32x2*)(P + row * LDP + 2048 + cbase + cb2);
;             f32x4 va = *(LAS f32x4*)(U + t * 128 + ca), vb = *(LAS f32x4*)(U + t * 128 + cb2);
;             float sm = ((va[0] + va[1]) + (va[2] + va[3])) + ((vb[0] + vb[1]) + (vb[2] + vb[3]));
;             sm += __shfl_xor(sm, 1); sm += __shfl_xor(sm, 2); sm += __shfl_xor(sm, 4); sm += __shfl_xor(sm, 8);
;             const float mu = sm * (1.f / 128.f);
;             va = va - mu; vb = vb - mu;
;             float sq = dot4(va) + dot4(vb);
;             sq += __shfl_xor(sq, 1); sq += __shfl_xor(sq, 2); sq += __shfl_xor(sq, 4); sq += __shfl_xor(sq, 8);
;             const float rstd = rsqrtf(sq * (1.f / 128.f) + EPS_);
;             f32x4 oa = va * rstd * ga + ba, ob = vb * rstd * gb + bb;
;             oa[0] = siluf_(oa[0]) * siluf_(bflo(za.x)); oa[1] = siluf_(oa[1]) * siluf_(bfhi(za.x)); oa[2] = siluf_(oa[2]) * siluf_(bflo(za.y)); oa[3] = siluf_(oa[3]) * siluf_(bfhi(za.y));
;             ob[0] = siluf_(ob[0]) * siluf_(bflo(zb.x)); ob[1] = siluf_(ob[1]) * siluf_(bfhi(zb.x)); ob[2] = siluf_(ob[2]) * siluf_(bflo(zb.y)); ob[3] = siluf_(ob[3]) * siluf_(bfhi(zb.y));
	global_load_dwordx2 v[28:29], v[6:7], off
	v_lshl_add_u64 v[2:3], v[2:3], 0, s[18:19]
	ds_read_b128 v[20:23], v85
	ds_read_b128 v[16:19], v85 offset:256
	global_load_dwordx2 v[36:37], v[2:3], off offset:128
	s_add_u32 s26, s80, s12
	v_ashrrev_i32_e32 v27, 31, v26
	s_waitcnt lgkmcnt(1)
	v_mov_b32_e32 v6, v20
	s_waitcnt lgkmcnt(0)
	v_mov_b32_e32 v7, v16
	v_mov_b32_e32 v8, v21
	v_mov_b32_e32 v9, v17
	v_pk_add_f32 v[6:7], v[6:7], v[8:9]
	v_mov_b32_e32 v8, v22
	v_mov_b32_e32 v9, v18
	v_mov_b32_e32 v10, v23
	v_mov_b32_e32 v11, v19
	v_pk_add_f32 v[8:9], v[8:9], v[10:11]
	s_addc_u32 s27, s81, 0
	v_pk_add_f32 v[6:7], v[6:7], v[8:9]
	s_add_i32 s35, s35, s58
	v_add_f32_e32 v6, v6, v7
	ds_bpermute_b32 v7, v81, v6
	s_add_i32 s28, s28, s29
	s_waitcnt lgkmcnt(0)
	v_add_f32_e32 v2, v6, v7
	ds_bpermute_b32 v3, v82, v2
	s_waitcnt lgkmcnt(0)
	v_add_f32_e32 v6, v2, v3
	ds_bpermute_b32 v7, v83, v6
	global_load_dwordx4 v[8:11], v[0:1], off
	s_nop 0
	global_load_dwordx4 v[0:3], v[0:1], off offset:256
	s_waitcnt lgkmcnt(0)
	v_add_f32_e32 v30, v6, v7
	ds_bpermute_b32 v31, v84, v30
	global_load_dwordx4 v[12:15], v[4:5], off
	s_nop 0
	global_load_dwordx4 v[4:7], v[4:5], off offset:256
	s_waitcnt lgkmcnt(0)
	v_add_f32_e32 v30, v30, v31
	v_fmamk_f32 v21, v30, 0xbc000000, v21
	v_fmamk_f32 v17, v30, 0xbc000000, v17
	v_fmamk_f32 v39, v30, 0xbc000000, v23
	v_fmamk_f32 v38, v30, 0xbc000000, v22
	v_fmac_f32_e32 v20, 0xbc000000, v30
	v_fmamk_f32 v23, v30, 0xbc000000, v19
	v_fmamk_f32 v22, v30, 0xbc000000, v18
	v_fmac_f32_e32 v16, 0xbc000000, v30
	v_mov_b32_e32 v30, v21
	v_mov_b32_e32 v31, v17
	v_mov_b32_e32 v18, v20
	v_mov_b32_e32 v19, v16
	v_pk_mul_f32 v[30:31], v[30:31], v[30:31]
	v_mov_b32_e32 v32, v39
	v_mov_b32_e32 v33, v23
	v_pk_fma_f32 v[18:19], v[18:19], v[18:19], v[30:31]
	v_mov_b32_e32 v30, v38
	v_mov_b32_e32 v31, v22
	v_pk_mul_f32 v[32:33], v[32:33], v[32:33]
	s_waitcnt vmcnt(5)
	v_lshlrev_b32_e32 v50, 16, v28
	v_and_b32_e32 v51, 0xffff0000, v28
	v_mul_f32_e32 v28, 0xbfb8aa3b, v50
	v_pk_fma_f32 v[30:31], v[30:31], v[30:31], v[32:33]
	v_exp_f32_e32 v28, v28
	v_mul_f32_e32 v32, 0xbfb8aa3b, v51
	v_exp_f32_e32 v32, v32
	v_pk_add_f32 v[18:19], v[18:19], v[30:31]
	v_add_f32_e32 v28, 1.0, v28
	v_rcp_f32_e32 v52, v28
	v_add_f32_e32 v28, 1.0, v32
	v_rcp_f32_e32 v53, v28
	v_lshlrev_b32_e32 v54, 16, v29
	v_and_b32_e32 v55, 0xffff0000, v29
	ds_read_b128 v[28:31], v87
	ds_read_b128 v[32:35], v87 offset:256
	v_mul_f32_e32 v40, 0xbfb8aa3b, v54
	v_exp_f32_e32 v40, v40
	v_mul_f32_e32 v49, 0xbfb8aa3b, v55
	s_waitcnt lgkmcnt(1)
	v_mov_b32_e32 v56, v28
	s_waitcnt lgkmcnt(0)
	v_mov_b32_e32 v57, v32
	v_mov_b32_e32 v58, v29
	v_mov_b32_e32 v59, v33
	v_pk_add_f32 v[56:57], v[56:57], v[58:59]
	v_mov_b32_e32 v58, v30
	v_mov_b32_e32 v59, v34
	v_mov_b32_e32 v60, v31
	v_mov_b32_e32 v61, v35
	v_pk_add_f32 v[58:59], v[58:59], v[60:61]
	v_exp_f32_e32 v49, v49
	v_pk_add_f32 v[56:57], v[56:57], v[58:59]
	v_add_f32_e32 v40, 1.0, v40
	v_add_f32_e32 v58, v56, v57
	ds_bpermute_b32 v59, v81, v58
	v_rcp_f32_e32 v56, v40
	v_add_f32_e32 v40, 1.0, v49
	v_rcp_f32_e32 v57, v40
	v_pk_mul_f32 v[50:51], v[52:53], v[50:51]
	s_waitcnt lgkmcnt(0)
	v_add_f32_e32 v40, v58, v59
	ds_bpermute_b32 v49, v82, v40
	s_waitcnt vmcnt(4)
	v_lshlrev_b32_e32 v58, 16, v36
	v_mul_f32_e32 v59, 0xbfb8aa3b, v58
	v_exp_f32_e32 v60, v59
	v_and_b32_e32 v59, 0xffff0000, v36
	s_waitcnt lgkmcnt(0)
	v_add_f32_e32 v36, v40, v49
	ds_bpermute_b32 v40, v83, v36
	v_add_f32_e32 v49, 1.0, v60
	v_mul_f32_e32 v60, 0xbfb8aa3b, v59
	v_exp_f32_e32 v61, v60
	v_rcp_f32_e32 v60, v49
	s_waitcnt lgkmcnt(0)
	v_add_f32_e32 v40, v36, v40
	ds_bpermute_b32 v49, v84, v40
	v_add_f32_e32 v36, 1.0, v61
	v_rcp_f32_e32 v61, v36
	v_pk_mul_f32 v[52:53], v[56:57], v[54:55]
	v_lshlrev_b32_e32 v36, 16, v37
	s_waitcnt lgkmcnt(0)
	v_add_f32_e32 v40, v40, v49
	v_fmamk_f32 v29, v40, 0xbc000000, v29
	v_fmamk_f32 v33, v40, 0xbc000000, v33
	v_fmamk_f32 v31, v40, 0xbc000000, v31
	v_fmac_f32_e32 v28, 0xbc000000, v40
	v_fmamk_f32 v35, v40, 0xbc000000, v35
	v_fmac_f32_e32 v32, 0xbc000000, v40
	v_mov_b32_e32 v64, v29
	v_mov_b32_e32 v65, v33
	v_fmamk_f32 v30, v40, 0xbc000000, v30
	v_fmamk_f32 v34, v40, 0xbc000000, v34
	v_mov_b32_e32 v62, v28
	v_mov_b32_e32 v63, v32
	v_pk_mul_f32 v[64:65], v[64:65], v[64:65]
	v_mov_b32_e32 v66, v31
	v_mov_b32_e32 v67, v35
	v_pk_fma_f32 v[62:63], v[62:63], v[62:63], v[64:65]
	v_mov_b32_e32 v64, v30
	v_mov_b32_e32 v65, v34
	v_pk_mul_f32 v[66:67], v[66:67], v[66:67]
	v_pk_mul_f32 v[54:55], v[60:61], v[58:59]
	v_pk_fma_f32 v[64:65], v[64:65], v[64:65], v[66:67]
	v_and_b32_e32 v37, 0xffff0000, v37
	v_pk_add_f32 v[62:63], v[62:63], v[64:65]
	v_mov_b32_e32 v65, v18
	v_mov_b32_e32 v64, v62
	v_mov_b32_e32 v18, v63
	v_pk_add_f32 v[18:19], v[64:65], v[18:19]
	ds_bpermute_b32 v63, v81, v19
	ds_bpermute_b32 v62, v81, v18
	v_mul_f32_e32 v40, 0xbfb8aa3b, v36
	v_exp_f32_e32 v40, v40
	v_mul_f32_e32 v49, 0xbfb8aa3b, v37
	v_exp_f32_e32 v49, v49
	s_waitcnt lgkmcnt(0)
	v_pk_add_f32 v[18:19], v[18:19], v[62:63]
	ds_bpermute_b32 v63, v82, v19
	ds_bpermute_b32 v62, v82, v18
	v_add_f32_e32 v40, 1.0, v40
	v_rcp_f32_e32 v64, v40
	v_add_f32_e32 v40, 1.0, v49
	v_rcp_f32_e32 v65, v40
	s_waitcnt lgkmcnt(0)
	v_pk_add_f32 v[18:19], v[18:19], v[62:63]
	ds_bpermute_b32 v63, v83, v19
	ds_bpermute_b32 v62, v83, v18
	v_pk_mul_f32 v[36:37], v[64:65], v[36:37]
	s_waitcnt lgkmcnt(0)
	v_pk_add_f32 v[56:57], v[18:19], v[62:63]
	ds_bpermute_b32 v59, v84, v57
	ds_bpermute_b32 v58, v84, v56
	v_lshlrev_b64 v[18:19], 12, v[26:27]
	v_mov_b64_e32 v[26:27], s[22:23]
	v_lshl_add_u64 v[18:19], s[26:27], 0, v[18:19]
	v_lshl_add_u64 v[60:61], v[18:19], 0, v[46:47]
	s_waitcnt lgkmcnt(0)
; DI float siluf_(float x) { return x * frcp(1.f + fexp(-x)); }
; DI u32x2 pack4(const f32x4 a) { u32x2 w; w.x = pk2(a[0], a[1]); w.y = pk2(a[2], a[3]); return w; }
; DI float dot4(const f32x4 a) { return (a[0] * a[0] + a[1] * a[1]) + (a[2] * a[2] + a[3] * a[3]); }
; DI void conv_item(LAS unsigned char* lds, int item, const bf16_t* P, const float* cw, const float* cb, const float* lng, const float* lnb, bf16_t* MIX) {
;     ...
;             const float mu = sm * (1.f / 128.f);
;             va = va - mu; vb = vb - mu;
;             float sq = dot4(va) + dot4(vb);
;             sq += __shfl_xor(sq, 1); sq += __shfl_xor(sq, 2); sq += __shfl_xor(sq, 4); sq += __shfl_xor(sq, 8);
;             const float rstd = rsqrtf(sq * (1.f / 128.f) + EPS_);
;             f32x4 oa = va * rstd * ga + ba, ob = vb * rstd * gb + bb;
;             oa[0] = siluf_(oa[0]) * siluf_(bflo(za.x)); oa[1] = siluf_(oa[1]) * siluf_(bfhi(za.x)); oa[2] = siluf_(oa[2]) * siluf_(bflo(za.y)); oa[3] = siluf_(oa[3]) * siluf_(bfhi(za.y));
;             ob[0] = siluf_(ob[0]) * siluf_(bflo(zb.x)); ob[1] = siluf_(ob[1]) * siluf_(bfhi(zb.x)); ob[2] = siluf_(ob[2]) * siluf_(bflo(zb.y)); ob[3] = siluf_(ob[3]) * siluf_(bfhi(zb.y));
;             *(u32x2*)(MIX + row * DM + cbase + ca) = pack4(oa); *(u32x2*)(MIX + row * DM + cbase + cb2) = pack4(ob);
	v_pk_add_f32 v[56:57], v[56:57], v[58:59]
	v_add_u32_e32 v18, s36, v86
	v_pk_fma_f32 v[56:57], v[56:57], s[20:21], v[26:27] op_sel_hi:[1,0,0]
	v_mad_i64_i32 v[58:59], s[38:39], v18, s30, v[24:25]
	v_mul_f32_e32 v19, 0x4b800000, v57
	v_cmp_gt_f32_e32 vcc, s34, v57
	v_lshl_add_u64 v[58:59], v[58:59], 0, s[12:13]
	v_lshl_add_u64 v[58:59], v[58:59], 0, v[46:47]
	v_cndmask_b32_e32 v19, v57, v19, vcc
	v_rsq_f32_e32 v19, v19
	s_nop 0
	v_mul_f32_e32 v40, 0x45800000, v19
	v_cndmask_b32_e32 v40, v19, v40, vcc
	v_pk_mul_f32 v[20:21], v[20:21], v[40:41] op_sel_hi:[1,0]
	v_pk_mul_f32 v[38:39], v[38:39], v[40:41] op_sel_hi:[1,0]
	s_waitcnt vmcnt(1)
	v_pk_fma_f32 v[20:21], v[8:9], v[20:21], v[12:13]
	v_pk_fma_f32 v[38:39], v[10:11], v[38:39], v[14:15]
	v_mul_f32_e32 v19, 0xbfb8aa3b, v20
	v_exp_f32_e32 v19, v19
	v_mul_f32_e32 v49, 0xbfb8aa3b, v21
	v_exp_f32_e32 v49, v49
	v_pk_mul_f32 v[16:17], v[16:17], v[40:41] op_sel_hi:[1,0]
	v_add_f32_e32 v19, 1.0, v19
	v_rcp_f32_e32 v62, v19
	v_add_f32_e32 v19, 1.0, v49
	v_rcp_f32_e32 v63, v19
	v_mul_f32_e32 v19, 0xbfb8aa3b, v38
	v_pk_mul_f32 v[22:23], v[22:23], v[40:41] op_sel_hi:[1,0]
	v_exp_f32_e32 v19, v19
	v_mul_f32_e32 v40, 0xbfb8aa3b, v39
	v_exp_f32_e32 v40, v40
	v_pk_mul_f32 v[20:21], v[20:21], v[62:63]
	v_add_f32_e32 v19, 1.0, v19
	s_waitcnt vmcnt(0)
	v_pk_fma_f32 v[16:17], v[0:1], v[16:17], v[4:5]
	v_pk_mul_f32 v[20:21], v[50:51], v[20:21]
	v_rcp_f32_e32 v50, v19
	v_add_f32_e32 v19, 1.0, v40
	v_rcp_f32_e32 v51, v19
	v_mul_f32_e32 v19, 0xbfb8aa3b, v16
	v_exp_f32_e32 v19, v19
	v_mul_f32_e32 v40, 0xbfb8aa3b, v17
	v_exp_f32_e32 v40, v40
	v_pk_fma_f32 v[22:23], v[2:3], v[22:23], v[6:7]
	v_add_f32_e32 v19, 1.0, v19
	v_pk_mul_f32 v[38:39], v[38:39], v[50:51]
	v_rcp_f32_e32 v50, v19
	v_add_f32_e32 v19, 1.0, v40
	v_mul_f32_e32 v40, 0xbfb8aa3b, v22
	v_exp_f32_e32 v40, v40
	v_mul_f32_e32 v49, 0xbfb8aa3b, v23
	v_exp_f32_e32 v49, v49
	v_rcp_f32_e32 v51, v19
	v_add_f32_e32 v19, 1.0, v40
	v_rcp_f32_e32 v62, v19
	v_add_f32_e32 v19, 1.0, v49
	v_rcp_f32_e32 v63, v19
	v_pk_mul_f32 v[16:17], v[16:17], v[50:51]
	v_pk_mul_f32 v[38:39], v[52:53], v[38:39]
	v_pk_mul_f32 v[16:17], v[54:55], v[16:17]
	v_pk_mul_f32 v[22:23], v[22:23], v[62:63]
	v_cvt_pk_bf16_f32 v16, v16, v17
	v_pk_mul_f32 v[22:23], v[36:37], v[22:23]
	v_cvt_pk_bf16_f32 v20, v20, v21
	v_cvt_pk_bf16_f32 v17, v22, v23
	v_cvt_pk_bf16_f32 v21, v38, v39
	global_store_dwordx2 v[60:61], v[16:17], off offset:128
	v_add_co_u32_e32 v16, vcc, s31, v58
	global_store_dwordx2 v[60:61], v[20:21], off
	s_nop 0
	v_addc_co_u32_e32 v17, vcc, 0, v59, vcc
	global_load_dwordx2 v[16:17], v[16:17], off
	v_lshl_add_u64 v[20:21], v[58:59], 0, s[18:19]
	global_load_dwordx2 v[20:21], v[20:21], off offset:128
	v_mul_f32_e32 v19, 0x4b800000, v56
	v_cmp_gt_f32_e32 vcc, s34, v56
	s_waitcnt vmcnt(1)
	v_lshlrev_b32_e32 v36, 16, v16
	v_cndmask_b32_e32 v19, v56, v19, vcc
	v_rsq_f32_e32 v22, v19
	v_mul_f32_e32 v37, 0xbfb8aa3b, v36
	v_exp_f32_e32 v38, v37
	v_and_b32_e32 v37, 0xffff0000, v16
	v_mul_f32_e32 v23, 0x45800000, v22
	v_cndmask_b32_e32 v22, v22, v23, vcc
	v_pk_mul_f32 v[28:29], v[28:29], v[22:23] op_sel_hi:[1,0]
	v_pk_mul_f32 v[30:31], v[30:31], v[22:23] op_sel_hi:[1,0]
	v_pk_fma_f32 v[28:29], v[8:9], v[28:29], v[12:13]
	v_pk_mul_f32 v[32:33], v[32:33], v[22:23] op_sel_hi:[1,0]
	v_pk_mul_f32 v[22:23], v[34:35], v[22:23] op_sel_hi:[1,0]
	v_mul_f32_e32 v34, 0xbfb8aa3b, v28
	v_mul_f32_e32 v35, 0xbfb8aa3b, v29
	v_exp_f32_e32 v34, v34
	v_exp_f32_e32 v35, v35
	v_pk_fma_f32 v[30:31], v[10:11], v[30:31], v[14:15]
	v_mul_f32_e32 v16, 0xbfb8aa3b, v37
	v_add_f32_e32 v34, 1.0, v34
	v_add_f32_e32 v35, 1.0, v35
	v_rcp_f32_e32 v34, v34
	v_rcp_f32_e32 v35, v35
	v_exp_f32_e32 v16, v16
	v_pk_fma_f32 v[32:33], v[0:1], v[32:33], v[4:5]
	v_add_f32_e32 v38, 1.0, v38
	v_pk_mul_f32 v[28:29], v[28:29], v[34:35]
	v_mul_f32_e32 v34, 0xbfb8aa3b, v30
	v_exp_f32_e32 v34, v34
	v_mul_f32_e32 v35, 0xbfb8aa3b, v31
	v_exp_f32_e32 v35, v35
	v_add_f32_e32 v16, 1.0, v16
	v_rcp_f32_e32 v39, v16
	v_add_f32_e32 v16, 1.0, v34
	v_lshlrev_b32_e32 v34, 16, v17
	v_add_f32_e32 v40, 1.0, v35
	v_and_b32_e32 v35, 0xffff0000, v17
	v_mul_f32_e32 v17, 0xbfb8aa3b, v34
	v_exp_f32_e32 v49, v17
	v_mul_f32_e32 v17, 0xbfb8aa3b, v35
	v_exp_f32_e32 v51, v17
	v_rcp_f32_e32 v17, v40
	v_add_f32_e32 v40, 1.0, v49
	v_rcp_f32_e32 v50, v40
	v_add_f32_e32 v40, 1.0, v51
	v_rcp_f32_e32 v16, v16
	v_rcp_f32_e32 v51, v40
	v_rcp_f32_e32 v38, v38
	v_pk_fma_f32 v[22:23], v[2:3], v[22:23], v[6:7]
	v_pk_mul_f32 v[16:17], v[30:31], v[16:17]
	v_pk_mul_f32 v[30:31], v[50:51], v[34:35]
	v_mul_f32_e32 v34, 0xbfb8aa3b, v32
	v_mul_f32_e32 v35, 0xbfb8aa3b, v33
	v_exp_f32_e32 v34, v34
	v_exp_f32_e32 v35, v35
	v_pk_mul_f32 v[16:17], v[30:31], v[16:17]
	v_pk_mul_f32 v[36:37], v[38:39], v[36:37]
	v_add_f32_e32 v30, 1.0, v34
	v_add_f32_e32 v31, 1.0, v35
	v_rcp_f32_e32 v30, v30
	v_rcp_f32_e32 v31, v31
	s_waitcnt vmcnt(0)
; #define LAS __attribute__((address_space(3)))
; DI float siluf_(float x) { return x * frcp(1.f + fexp(-x)); }
; DI u32x2 pack4(const f32x4 a) { u32x2 w; w.x = pk2(a[0], a[1]); w.y = pk2(a[2], a[3]); return w; }
; DI float dot4(const f32x4 a) { return (a[0] * a[0] + a[1] * a[1]) + (a[2] * a[2] + a[3] * a[3]); }
; DI void conv_item(LAS unsigned char* lds, int item, const bf16_t* P, const float* cw, const float* cb, const float* lng, const float* lnb, bf16_t* MIX) {
;     ...
;             const int t = wid * 16 + it * 4 + ts;
;             const size_t row = (size_t)(tt0 + t);
;             const u32x2 za = *(const u32x2*)(P + row * LDP + 2048 + cbase + ca), zb = *(const u32x2*)(P + row * LDP + 2048 + cbase + cb2);
;             f32x4 va = *(LAS f32x4*)(U + t * 128 + ca), vb = *(LAS f32x4*)(U + t * 128 + cb2);
;             float sm = ((va[0] + va[1]) + (va[2] + va[3])) + ((vb[0] + vb[1]) + (vb[2] + vb[3]));
;             sm += __shfl_xor(sm, 1); sm += __shfl_xor(sm, 2); sm += __shfl_xor(sm, 4); sm += __shfl_xor(sm, 8);
;             const float mu = sm * (1.f / 128.f);
;             va = va - mu; vb = vb - mu;
;             float sq = dot4(va) + dot4(vb);
;             sq += __shfl_xor(sq, 1); sq += __shfl_xor(sq, 2); sq += __shfl_xor(sq, 4); sq += __shfl_xor(sq, 8);
;             const float rstd = rsqrtf(sq * (1.f / 128.f) + EPS_);
;             f32x4 oa = va * rstd * ga + ba, ob = vb * rstd * gb + bb;
;             oa[0] = siluf_(oa[0]) * siluf_(bflo(za.x)); oa[1] = siluf_(oa[1]) * siluf_(bfhi(za.x)); oa[2] = siluf_(oa[2]) * siluf_(bflo(za.y)); oa[3] = siluf_(oa[3]) * siluf_(bfhi(za.y));
;             ob[0] = siluf_(ob[0]) * siluf_(bflo(zb.x)); ob[1] = siluf_(ob[1]) * siluf_(bfhi(zb.x)); ob[2] = siluf_(ob[2]) * siluf_(bflo(zb.y)); ob[3] = siluf_(ob[3]) * siluf_(bfhi(zb.y));
;             *(u32x2*)(MIX + row * DM + cbase + ca) = pack4(oa); *(u32x2*)(MIX + row * DM + cbase + cb2) = pack4(ob);
	v_lshlrev_b32_e32 v34, 16, v20
	v_mul_f32_e32 v35, 0xbfb8aa3b, v34
	v_pk_mul_f32 v[28:29], v[36:37], v[28:29]
	v_exp_f32_e32 v36, v35
	v_and_b32_e32 v35, 0xffff0000, v20
	v_mul_f32_e32 v20, 0xbfb8aa3b, v35
	v_exp_f32_e32 v20, v20
	v_pk_mul_f32 v[30:31], v[32:33], v[30:31]
	v_mul_f32_e32 v32, 0xbfb8aa3b, v22
	v_exp_f32_e32 v32, v32
	v_mul_f32_e32 v33, 0xbfb8aa3b, v23
	v_exp_f32_e32 v33, v33
	v_add_f32_e32 v20, 1.0, v20
	v_rcp_f32_e32 v37, v20
	v_add_f32_e32 v20, 1.0, v32
	v_lshlrev_b32_e32 v32, 16, v21
	v_add_f32_e32 v38, 1.0, v33
	v_and_b32_e32 v33, 0xffff0000, v21
	v_mul_f32_e32 v21, 0xbfb8aa3b, v32
	v_exp_f32_e32 v39, v21
	v_mul_f32_e32 v21, 0xbfb8aa3b, v33
	v_exp_f32_e32 v40, v21
	v_rcp_f32_e32 v21, v38
	v_add_f32_e32 v38, 1.0, v39
	v_add_f32_e32 v36, 1.0, v36
	v_add_f32_e32 v39, 1.0, v40
	v_rcp_f32_e32 v20, v20
	v_rcp_f32_e32 v38, v38
	v_rcp_f32_e32 v39, v39
	v_rcp_f32_e32 v36, v36
	v_ashrrev_i32_e32 v19, 31, v18
	v_pk_mul_f32 v[20:21], v[22:23], v[20:21]
	v_pk_mul_f32 v[22:23], v[38:39], v[32:33]
	v_pk_mul_f32 v[34:35], v[36:37], v[34:35]
	v_pk_mul_f32 v[20:21], v[22:23], v[20:21]
	v_cvt_pk_bf16_f32 v23, v16, v17
	v_lshlrev_b64 v[16:17], 12, v[18:19]
	v_pk_mul_f32 v[30:31], v[34:35], v[30:31]
	v_lshl_add_u64 v[16:17], s[26:27], 0, v[16:17]
	v_cvt_pk_bf16_f32 v22, v28, v29
	v_lshl_add_u64 v[16:17], v[16:17], 0, v[46:47]
	v_cvt_pk_bf16_f32 v18, v30, v31
	v_cvt_pk_bf16_f32 v19, v20, v21
	v_add_u32_e32 v28, s36, v88
	global_store_dwordx2 v[16:17], v[22:23], off
	global_store_dwordx2 v[16:17], v[18:19], off offset:128
	v_mad_i64_i32 v[16:17], s[38:39], v28, s30, v[24:25]
	v_lshl_add_u64 v[16:17], v[16:17], 0, s[12:13]
	v_lshl_add_u64 v[30:31], v[16:17], 0, v[46:47]
	v_add_co_u32_e32 v16, vcc, s31, v30
	s_nop 1
	v_addc_co_u32_e32 v17, vcc, 0, v31, vcc
	global_load_dwordx2 v[32:33], v[16:17], off
	ds_read_b128 v[20:23], v89
	ds_read_b128 v[16:19], v89 offset:256
	v_lshl_add_u64 v[30:31], v[30:31], 0, s[18:19]
	s_waitcnt lgkmcnt(1)
	v_mov_b32_e32 v34, v20
	s_waitcnt lgkmcnt(0)
	v_mov_b32_e32 v35, v16
	v_mov_b32_e32 v36, v21
	v_mov_b32_e32 v37, v17
	v_pk_add_f32 v[34:35], v[34:35], v[36:37]
	v_mov_b32_e32 v36, v22
	v_mov_b32_e32 v37, v18
	v_mov_b32_e32 v38, v23
	v_mov_b32_e32 v39, v19
	v_pk_add_f32 v[36:37], v[36:37], v[38:39]
	global_load_dwordx2 v[38:39], v[30:31], off offset:128
	v_pk_add_f32 v[34:35], v[34:35], v[36:37]
	s_waitcnt vmcnt(1)
	v_lshlrev_b32_e32 v52, 16, v32
	v_add_f32_e32 v29, v34, v35
	ds_bpermute_b32 v34, v81, v29
	v_and_b32_e32 v53, 0xffff0000, v32
	v_mul_f32_e32 v32, 0xbfb8aa3b, v52
	v_exp_f32_e32 v32, v32
	v_lshlrev_b32_e32 v56, 16, v33
	s_waitcnt lgkmcnt(0)
	v_add_f32_e32 v29, v29, v34
	ds_bpermute_b32 v30, v82, v29
	v_and_b32_e32 v57, 0xffff0000, v33
	v_mul_f32_e32 v40, 0xbfb8aa3b, v56
	v_exp_f32_e32 v40, v40
	v_mul_f32_e32 v49, 0xbfb8aa3b, v57
	s_waitcnt lgkmcnt(0)
	v_add_f32_e32 v29, v29, v30
	ds_bpermute_b32 v30, v83, v29
	v_exp_f32_e32 v49, v49
	v_add_f32_e32 v40, 1.0, v40
	s_waitcnt lgkmcnt(0)
	v_add_f32_e32 v30, v29, v30
	ds_bpermute_b32 v31, v84, v30
	v_ashrrev_i32_e32 v29, 31, v28
	s_waitcnt lgkmcnt(0)
	v_add_f32_e32 v30, v30, v31
	v_fmamk_f32 v21, v30, 0xbc000000, v21
	v_fmamk_f32 v17, v30, 0xbc000000, v17
	v_fmamk_f32 v23, v30, 0xbc000000, v23
	v_fmamk_f32 v22, v30, 0xbc000000, v22
	v_fmac_f32_e32 v20, 0xbc000000, v30
	v_fmamk_f32 v51, v30, 0xbc000000, v19
	v_fmamk_f32 v50, v30, 0xbc000000, v18
	v_fmac_f32_e32 v16, 0xbc000000, v30
	v_mov_b32_e32 v30, v21
	v_mov_b32_e32 v31, v17
	v_mov_b32_e32 v18, v20
	v_mov_b32_e32 v19, v16
	v_pk_mul_f32 v[30:31], v[30:31], v[30:31]
	v_mov_b32_e32 v34, v23
	v_mov_b32_e32 v35, v51
	v_pk_fma_f32 v[18:19], v[18:19], v[18:19], v[30:31]
	v_mov_b32_e32 v30, v22
	v_mov_b32_e32 v31, v50
	v_pk_mul_f32 v[34:35], v[34:35], v[34:35]
	s_nop 0
	v_pk_fma_f32 v[30:31], v[30:31], v[30:31], v[34:35]
	v_mul_f32_e32 v34, 0xbfb8aa3b, v53
	v_exp_f32_e32 v34, v34
	v_pk_add_f32 v[18:19], v[18:19], v[30:31]
	v_add_f32_e32 v30, 1.0, v32
	v_rcp_f32_e32 v54, v30
	v_add_f32_e32 v30, 1.0, v34
	v_rcp_f32_e32 v55, v30
	ds_read_b128 v[30:33], v91
	ds_read_b128 v[34:37], v91 offset:256
	v_pk_mul_f32 v[52:53], v[54:55], v[52:53]
	s_waitcnt lgkmcnt(1)
	v_mov_b32_e32 v58, v30
	s_waitcnt lgkmcnt(0)
	v_mov_b32_e32 v59, v34
	v_mov_b32_e32 v60, v31
	v_mov_b32_e32 v61, v35
	v_pk_add_f32 v[58:59], v[58:59], v[60:61]
	v_mov_b32_e32 v60, v32
	v_mov_b32_e32 v61, v36
	v_mov_b32_e32 v62, v33
	v_mov_b32_e32 v63, v37
	v_pk_add_f32 v[60:61], v[60:61], v[62:63]
	s_nop 0
	v_pk_add_f32 v[58:59], v[58:59], v[60:61]
	s_nop 0
	v_add_f32_e32 v60, v58, v59
	ds_bpermute_b32 v61, v81, v60
	v_rcp_f32_e32 v58, v40
	v_add_f32_e32 v40, 1.0, v49
	v_rcp_f32_e32 v59, v40
	s_waitcnt lgkmcnt(0)
	v_add_f32_e32 v40, v60, v61
	ds_bpermute_b32 v49, v82, v40
	s_waitcnt vmcnt(0)
	v_lshlrev_b32_e32 v60, 16, v38
	v_mul_f32_e32 v61, 0xbfb8aa3b, v60
	v_exp_f32_e32 v62, v61
	v_and_b32_e32 v61, 0xffff0000, v38
	s_waitcnt lgkmcnt(0)
	v_add_f32_e32 v38, v40, v49
	ds_bpermute_b32 v40, v83, v38
	v_add_f32_e32 v49, 1.0, v62
	v_mul_f32_e32 v62, 0xbfb8aa3b, v61
	v_exp_f32_e32 v63, v62
	v_rcp_f32_e32 v62, v49
	s_waitcnt lgkmcnt(0)
	v_add_f32_e32 v40, v38, v40
	ds_bpermute_b32 v49, v84, v40
	v_add_f32_e32 v38, 1.0, v63
	v_rcp_f32_e32 v63, v38
	v_pk_mul_f32 v[54:55], v[58:59], v[56:57]
	v_lshlrev_b32_e32 v38, 16, v39
	s_waitcnt lgkmcnt(0)
; #define LAS __attribute__((address_space(3)))
; DI float siluf_(float x) { return x * frcp(1.f + fexp(-x)); }
; DI u32x2 pack4(const f32x4 a) { u32x2 w; w.x = pk2(a[0], a[1]); w.y = pk2(a[2], a[3]); return w; }
; DI float dot4(const f32x4 a) { return (a[0] * a[0] + a[1] * a[1]) + (a[2] * a[2] + a[3] * a[3]); }
; DI void conv_item(LAS unsigned char* lds, int item, const bf16_t* P, const float* cw, const float* cb, const float* lng, const float* lnb, bf16_t* MIX) {
;     ...
;             const int t = wid * 16 + it * 4 + ts;
;             const size_t row = (size_t)(tt0 + t);
;             const u32x2 za = *(const u32x2*)(P + row * LDP + 2048 + cbase + ca), zb = *(const u32x2*)(P + row * LDP + 2048 + cbase + cb2);
;             f32x4 va = *(LAS f32x4*)(U + t * 128 + ca), vb = *(LAS f32x4*)(U + t * 128 + cb2);
;             float sm = ((va[0] + va[1]) + (va[2] + va[3])) + ((vb[0] + vb[1]) + (vb[2] + vb[3]));
;             sm += __shfl_xor(sm, 1); sm += __shfl_xor(sm, 2); sm += __shfl_xor(sm, 4); sm += __shfl_xor(sm, 8);
;             const float mu = sm * (1.f / 128.f);
;             va = va - mu; vb = vb - mu;
;             float sq = dot4(va) + dot4(vb);
;             sq += __shfl_xor(sq, 1); sq += __shfl_xor(sq, 2); sq += __shfl_xor(sq, 4); sq += __shfl_xor(sq, 8);
;             const float rstd = rsqrtf(sq * (1.f / 128.f) + EPS_);
;             f32x4 oa = va * rstd * ga + ba, ob = vb * rstd * gb + bb;
;             oa[0] = siluf_(oa[0]) * siluf_(bflo(za.x)); oa[1] = siluf_(oa[1]) * siluf_(bfhi(za.x)); oa[2] = siluf_(oa[2]) * siluf_(bflo(za.y)); oa[3] = siluf_(oa[3]) * siluf_(bfhi(za.y));
;             ob[0] = siluf_(ob[0]) * siluf_(bflo(zb.x)); ob[1] = siluf_(ob[1]) * siluf_(bfhi(zb.x)); ob[2] = siluf_(ob[2]) * siluf_(bflo(zb.y)); ob[3] = siluf_(ob[3]) * siluf_(bfhi(zb.y));
;             *(u32x2*)(MIX + row * DM + cbase + ca) = pack4(oa); *(u32x2*)(MIX + row * DM + cbase + cb2) = pack4(ob);
	v_add_f32_e32 v40, v40, v49
	v_fmamk_f32 v31, v40, 0xbc000000, v31
	v_fmamk_f32 v35, v40, 0xbc000000, v35
	v_fmamk_f32 v33, v40, 0xbc000000, v33
	v_fmac_f32_e32 v30, 0xbc000000, v40
	v_fmamk_f32 v37, v40, 0xbc000000, v37
	v_fmac_f32_e32 v34, 0xbc000000, v40
	v_mov_b32_e32 v66, v31
	v_mov_b32_e32 v67, v35
	v_fmamk_f32 v32, v40, 0xbc000000, v32
	v_fmamk_f32 v36, v40, 0xbc000000, v36
	v_mov_b32_e32 v64, v30
	v_mov_b32_e32 v65, v34
	v_pk_mul_f32 v[66:67], v[66:67], v[66:67]
	v_mov_b32_e32 v92, v33
	v_mov_b32_e32 v93, v37
	v_pk_fma_f32 v[64:65], v[64:65], v[64:65], v[66:67]
	v_mov_b32_e32 v66, v32
	v_mov_b32_e32 v67, v36
	v_pk_mul_f32 v[92:93], v[92:93], v[92:93]
	v_pk_mul_f32 v[56:57], v[62:63], v[60:61]
	v_pk_fma_f32 v[66:67], v[66:67], v[66:67], v[92:93]
	v_and_b32_e32 v39, 0xffff0000, v39
	v_pk_add_f32 v[64:65], v[64:65], v[66:67]
	v_mov_b32_e32 v67, v18
	v_mov_b32_e32 v66, v64
	v_mov_b32_e32 v18, v65
	v_pk_add_f32 v[18:19], v[66:67], v[18:19]
	ds_bpermute_b32 v65, v81, v19
	ds_bpermute_b32 v64, v81, v18
	v_mul_f32_e32 v40, 0xbfb8aa3b, v38
	v_exp_f32_e32 v40, v40
	v_mul_f32_e32 v49, 0xbfb8aa3b, v39
	v_exp_f32_e32 v49, v49
	s_waitcnt lgkmcnt(0)
	v_pk_add_f32 v[18:19], v[18:19], v[64:65]
	ds_bpermute_b32 v65, v82, v19
	ds_bpermute_b32 v64, v82, v18
	v_add_f32_e32 v40, 1.0, v40
	v_rcp_f32_e32 v66, v40
	v_add_f32_e32 v40, 1.0, v49
	v_rcp_f32_e32 v67, v40
	s_waitcnt lgkmcnt(0)
	v_pk_add_f32 v[18:19], v[18:19], v[64:65]
	ds_bpermute_b32 v65, v83, v19
	ds_bpermute_b32 v64, v83, v18
	v_pk_mul_f32 v[38:39], v[66:67], v[38:39]
	s_waitcnt lgkmcnt(0)
	v_pk_add_f32 v[58:59], v[18:19], v[64:65]
	ds_bpermute_b32 v61, v84, v59
	ds_bpermute_b32 v60, v84, v58
	v_lshlrev_b64 v[18:19], 12, v[28:29]
	v_lshl_add_u64 v[18:19], s[26:27], 0, v[18:19]
	v_lshl_add_u64 v[28:29], v[18:19], 0, v[46:47]
	v_add_u32_e32 v18, s36, v90
	s_waitcnt lgkmcnt(0)
	v_pk_add_f32 v[58:59], v[58:59], v[60:61]
	v_mad_i64_i32 v[24:25], s[36:37], v18, s30, v[24:25]
	v_pk_fma_f32 v[26:27], v[58:59], s[20:21], v[26:27] op_sel_hi:[1,0,0]
	v_lshl_add_u64 v[24:25], v[24:25], 0, s[12:13]
	v_mul_f32_e32 v19, 0x4b800000, v27
	v_cmp_gt_f32_e32 vcc, s34, v27
	v_lshl_add_u64 v[24:25], v[24:25], 0, v[46:47]
	s_add_i32 s21, s21, s23
	v_cndmask_b32_e32 v19, v27, v19, vcc
	v_rsq_f32_e32 v19, v19
	s_cmpk_gt_i32 s35, 0x1ff
	v_mul_f32_e32 v27, 0x45800000, v19
	v_cndmask_b32_e32 v40, v19, v27, vcc
	v_pk_mul_f32 v[20:21], v[20:21], v[40:41] op_sel_hi:[1,0]
	v_pk_mul_f32 v[22:23], v[22:23], v[40:41] op_sel_hi:[1,0]
	v_pk_fma_f32 v[20:21], v[8:9], v[20:21], v[12:13]
	v_pk_fma_f32 v[22:23], v[10:11], v[22:23], v[14:15]
	v_mul_f32_e32 v19, 0xbfb8aa3b, v20
	v_exp_f32_e32 v19, v19
	v_mul_f32_e32 v27, 0xbfb8aa3b, v21
	v_exp_f32_e32 v27, v27
	v_pk_mul_f32 v[16:17], v[16:17], v[40:41] op_sel_hi:[1,0]
	v_add_f32_e32 v19, 1.0, v19
	v_rcp_f32_e32 v58, v19
	v_add_f32_e32 v19, 1.0, v27
	v_rcp_f32_e32 v59, v19
	v_mul_f32_e32 v19, 0xbfb8aa3b, v22
	v_exp_f32_e32 v19, v19
	v_mul_f32_e32 v27, 0xbfb8aa3b, v23
	v_exp_f32_e32 v27, v27
	v_pk_mul_f32 v[20:21], v[20:21], v[58:59]
	v_add_f32_e32 v19, 1.0, v19
	v_pk_fma_f32 v[16:17], v[0:1], v[16:17], v[4:5]
	v_pk_mul_f32 v[20:21], v[52:53], v[20:21]
	v_rcp_f32_e32 v52, v19
	v_add_f32_e32 v19, 1.0, v27
	v_rcp_f32_e32 v53, v19
	v_mul_f32_e32 v19, 0xbfb8aa3b, v16
	v_exp_f32_e32 v19, v19
	v_mul_f32_e32 v27, 0xbfb8aa3b, v17
	v_exp_f32_e32 v27, v27
	v_pk_mul_f32 v[50:51], v[50:51], v[40:41] op_sel_hi:[1,0]
	v_add_f32_e32 v19, 1.0, v19
	v_pk_fma_f32 v[50:51], v[2:3], v[50:51], v[6:7]
	v_pk_mul_f32 v[22:23], v[22:23], v[52:53]
	v_rcp_f32_e32 v52, v19
	v_add_f32_e32 v19, 1.0, v27
	v_mul_f32_e32 v27, 0xbfb8aa3b, v50
	v_exp_f32_e32 v27, v27
	v_mul_f32_e32 v40, 0xbfb8aa3b, v51
	v_exp_f32_e32 v40, v40
	v_rcp_f32_e32 v53, v19
	v_add_f32_e32 v19, 1.0, v27
	v_rcp_f32_e32 v58, v19
	v_add_f32_e32 v19, 1.0, v40
	v_rcp_f32_e32 v59, v19
	v_pk_mul_f32 v[16:17], v[16:17], v[52:53]
	v_pk_mul_f32 v[22:23], v[54:55], v[22:23]
	v_pk_mul_f32 v[16:17], v[56:57], v[16:17]
	v_pk_mul_f32 v[50:51], v[50:51], v[58:59]
	v_cvt_pk_bf16_f32 v16, v16, v17
	v_pk_mul_f32 v[38:39], v[38:39], v[50:51]
	v_cvt_pk_bf16_f32 v20, v20, v21
	v_cvt_pk_bf16_f32 v17, v38, v39
	v_cvt_pk_bf16_f32 v21, v22, v23
	global_store_dwordx2 v[28:29], v[16:17], off offset:128
	v_add_co_u32_e32 v16, vcc, s31, v24
	global_store_dwordx2 v[28:29], v[20:21], off
	s_nop 0
	v_addc_co_u32_e32 v17, vcc, 0, v25, vcc
	global_load_dwordx2 v[16:17], v[16:17], off
	v_lshl_add_u64 v[20:21], v[24:25], 0, s[18:19]
	global_load_dwordx2 v[20:21], v[20:21], off offset:128
	v_mul_f32_e32 v19, 0x4b800000, v26
	v_cmp_gt_f32_e32 vcc, s34, v26
	s_nop 1
	v_cndmask_b32_e32 v19, v26, v19, vcc
	v_rsq_f32_e32 v22, v19
	v_ashrrev_i32_e32 v19, 31, v18
	v_mul_f32_e32 v23, 0x45800000, v22
	v_cndmask_b32_e32 v22, v22, v23, vcc
	v_pk_mul_f32 v[24:25], v[30:31], v[22:23] op_sel_hi:[1,0]
	v_pk_mul_f32 v[26:27], v[32:33], v[22:23] op_sel_hi:[1,0]
	v_pk_fma_f32 v[8:9], v[8:9], v[24:25], v[12:13]
	v_pk_fma_f32 v[10:11], v[10:11], v[26:27], v[14:15]
	v_pk_mul_f32 v[14:15], v[36:37], v[22:23] op_sel_hi:[1,0]
	v_pk_mul_f32 v[12:13], v[34:35], v[22:23] op_sel_hi:[1,0]
	v_pk_fma_f32 v[2:3], v[2:3], v[14:15], v[6:7]
	v_mul_f32_e32 v6, 0xbfb8aa3b, v8
	v_exp_f32_e32 v6, v6
	v_mul_f32_e32 v7, 0xbfb8aa3b, v9
	v_exp_f32_e32 v7, v7
	v_pk_fma_f32 v[0:1], v[0:1], v[12:13], v[4:5]
	v_add_f32_e32 v4, 1.0, v6
	v_rcp_f32_e32 v4, v4
	v_add_f32_e32 v5, 1.0, v7
	v_rcp_f32_e32 v5, v5
	s_waitcnt vmcnt(1)
; #define LAS __attribute__((address_space(3)))
; DI float sigmoidf_(float x) { return frcp(1.f + fexp(-x)); }
; DI float siluf_(float x) { return x * frcp(1.f + fexp(-x)); }
; DI u32x2 pack4(const f32x4 a) { u32x2 w; w.x = pk2(a[0], a[1]); w.y = pk2(a[2], a[3]); return w; }
; DI void conv_item(LAS unsigned char* lds, int item, const bf16_t* P, const float* cw, const float* cb, const float* lng, const float* lnb, bf16_t* MIX) {
;     ...
;             const int id = tid + 512 * j, row = id >> 4, c8 = (id & 15) * 8, tt = tt0 - 30 + row;
;             vv[j] = (u32x4){0u, 0u, 0u, 0u}; gv[j] = vv[j];
;             if (id < 158 * 16 && tt >= bstart) { vv[j] = *(const u32x4*)(P + (size_t)tt * LDP + cbase + c8); gv[j] = *(const u32x4*)(P + (size_t)tt * LDP + 1024 + cbase + c8); }
;         }
; #pragma unroll
;         for (int j = 0; j < 5; ++j) {
;             const int id = tid + 512 * j, row = id >> 4, c8 = (id & 15) * 8;
;             const u32x4 v = vv[j], gg = gv[j];
;             f32x4 u0, u1;
;             u0[0] = bflo(v.x) * sigmoidf_(bflo(gg.x)); u0[1] = bfhi(v.x) * sigmoidf_(bfhi(gg.x));
;             u0[2] = bflo(v.y) * sigmoidf_(bflo(gg.y)); u0[3] = bfhi(v.y) * sigmoidf_(bfhi(gg.y));
;             u1[0] = bflo(v.z) * sigmoidf_(bflo(gg.z)); u1[1] = bfhi(v.z) * sigmoidf_(bfhi(gg.z));
;             u1[2] = bflo(v.w) * sigmoidf_(bflo(gg.w)); u1[3] = bfhi(v.w) * sigmoidf_(bfhi(gg.w));
;             if (id < 158 * 16) { *(LAS f32x4*)(U + row * 128 + c8) = u0; *(LAS f32x4*)(U + row * 128 + c8 + 4) = u1; }
;         }
;     }
;     __syncthreads();
;     const int c = tid & 127, tq = tid >> 7;
;     float y[32];
;     {
;         float w[31];
; #pragma unroll
;         for (int k = 0; k < 31; ++k) w[k] = cw[k * 1024 + cbase + c];
;         const float bias = cb[cbase + c];
;     ...
;             oa[0] = siluf_(oa[0]) * siluf_(bflo(za.x)); oa[1] = siluf_(oa[1]) * siluf_(bfhi(za.x)); oa[2] = siluf_(oa[2]) * siluf_(bflo(za.y)); oa[3] = siluf_(oa[3]) * siluf_(bfhi(za.y));
;             ob[0] = siluf_(ob[0]) * siluf_(bflo(zb.x)); ob[1] = siluf_(ob[1]) * siluf_(bfhi(zb.x)); ob[2] = siluf_(ob[2]) * siluf_(bflo(zb.y)); ob[3] = siluf_(ob[3]) * siluf_(bfhi(zb.y));
;             *(u32x2*)(MIX + row * DM + cbase + ca) = pack4(oa); *(u32x2*)(MIX + row * DM + cbase + cb2) = pack4(ob);
;         }
;     }
;     __syncthreads();
	v_lshlrev_b32_e32 v6, 16, v16
	v_mul_f32_e32 v7, 0xbfb8aa3b, v6
	v_exp_f32_e32 v12, v7
	v_and_b32_e32 v7, 0xffff0000, v16
	v_mul_f32_e32 v13, 0xbfb8aa3b, v7
	v_exp_f32_e32 v13, v13
	v_pk_mul_f32 v[4:5], v[8:9], v[4:5]
	v_mul_f32_e32 v9, 0xbfb8aa3b, v10
	v_exp_f32_e32 v9, v9
	v_add_f32_e32 v8, 1.0, v13
	v_mul_f32_e32 v13, 0xbfb8aa3b, v11
	v_exp_f32_e32 v14, v13
	v_rcp_f32_e32 v13, v8
	v_add_f32_e32 v8, 1.0, v9
	v_and_b32_e32 v15, 0xffff0000, v17
	v_add_f32_e32 v9, 1.0, v14
	v_lshlrev_b32_e32 v14, 16, v17
	v_add_f32_e32 v12, 1.0, v12
	v_mul_f32_e32 v16, 0xbfb8aa3b, v14
	v_mul_f32_e32 v17, 0xbfb8aa3b, v15
	v_rcp_f32_e32 v12, v12
	v_exp_f32_e32 v16, v16
	v_exp_f32_e32 v17, v17
	v_rcp_f32_e32 v8, v8
	v_rcp_f32_e32 v9, v9
	v_add_f32_e32 v16, 1.0, v16
	v_add_f32_e32 v17, 1.0, v17
	v_pk_mul_f32 v[6:7], v[12:13], v[6:7]
	v_rcp_f32_e32 v16, v16
	v_rcp_f32_e32 v17, v17
	v_pk_mul_f32 v[4:5], v[6:7], v[4:5]
	v_pk_mul_f32 v[6:7], v[10:11], v[8:9]
	v_mul_f32_e32 v10, 0xbfb8aa3b, v0
	v_exp_f32_e32 v10, v10
	v_mul_f32_e32 v11, 0xbfb8aa3b, v1
	v_exp_f32_e32 v11, v11
	v_pk_mul_f32 v[8:9], v[16:17], v[14:15]
	s_waitcnt vmcnt(0)
	v_and_b32_e32 v15, 0xffff0000, v21
	v_pk_mul_f32 v[6:7], v[8:9], v[6:7]
	v_add_f32_e32 v8, 1.0, v10
	v_lshlrev_b32_e32 v10, 16, v20
	v_add_f32_e32 v9, 1.0, v11
	v_mul_f32_e32 v11, 0xbfb8aa3b, v10
	v_exp_f32_e32 v12, v11
	v_and_b32_e32 v11, 0xffff0000, v20
	v_mul_f32_e32 v13, 0xbfb8aa3b, v11
	v_rcp_f32_e32 v8, v8
	v_rcp_f32_e32 v9, v9
	v_exp_f32_e32 v13, v13
	v_mul_f32_e32 v17, 0xbfb8aa3b, v15
	v_exp_f32_e32 v17, v17
	v_pk_mul_f32 v[0:1], v[0:1], v[8:9]
	v_add_f32_e32 v8, 1.0, v13
	v_mul_f32_e32 v9, 0xbfb8aa3b, v2
	v_mul_f32_e32 v13, 0xbfb8aa3b, v3
	v_exp_f32_e32 v9, v9
	v_exp_f32_e32 v14, v13
	v_rcp_f32_e32 v13, v8
	v_add_f32_e32 v12, 1.0, v12
	v_add_f32_e32 v8, 1.0, v9
	v_add_f32_e32 v9, 1.0, v14
	v_lshlrev_b32_e32 v14, 16, v21
	v_mul_f32_e32 v16, 0xbfb8aa3b, v14
	v_exp_f32_e32 v16, v16
	v_add_f32_e32 v17, 1.0, v17
	v_rcp_f32_e32 v12, v12
	v_rcp_f32_e32 v8, v8
	v_add_f32_e32 v16, 1.0, v16
	v_rcp_f32_e32 v9, v9
	v_rcp_f32_e32 v16, v16
	v_rcp_f32_e32 v17, v17
	v_pk_mul_f32 v[10:11], v[12:13], v[10:11]
	v_pk_mul_f32 v[2:3], v[2:3], v[8:9]
	v_cvt_pk_bf16_f32 v4, v4, v5
	v_pk_mul_f32 v[8:9], v[16:17], v[14:15]
	v_cvt_pk_bf16_f32 v5, v6, v7
	v_lshlrev_b64 v[6:7], 12, v[18:19]
	v_pk_mul_f32 v[0:1], v[10:11], v[0:1]
	v_pk_mul_f32 v[2:3], v[8:9], v[2:3]
	v_lshl_add_u64 v[6:7], s[26:27], 0, v[6:7]
	v_lshl_add_u64 v[6:7], v[6:7], 0, v[46:47]
	v_cvt_pk_bf16_f32 v0, v0, v1
	v_cvt_pk_bf16_f32 v1, v2, v3
	global_store_dwordx2 v[6:7], v[4:5], off
	global_store_dwordx2 v[6:7], v[0:1], off offset:128
	s_barrier
	s_cbranch_scc1 .LBB0_532
.LBB0_518:
	s_and_b32 s36, s21, 0xffffff80
	s_sub_i32 s39, s36, 30
	s_and_b32 s38, s21, 0xfffff000
	v_add_u32_e32 v0, s39, v68
	s_and_b32 s37, s28, 0x380
	v_lshlrev_b32_e32 v250, 3, v252
	v_lshl_add_u32 v250, s37, 2, v250
	global_load_dwordx2 v[126:127], v250, s[14:15]
	s_add_u32 vcc_lo, s14, 0x1000
	s_addc_u32 vcc_hi, s15, 0
	global_load_dwordx2 v[128:129], v250, vcc
	s_add_u32 vcc_lo, s14, 0x2000
	s_addc_u32 vcc_hi, s15, 0
	global_load_dwordx2 v[130:131], v250, vcc
	s_add_u32 vcc_lo, s14, 0x3000
	s_addc_u32 vcc_hi, s15, 0
	global_load_dwordx2 v[132:133], v250, vcc
	s_add_u32 vcc_lo, s14, 0x4000
	s_addc_u32 vcc_hi, s15, 0
	global_load_dwordx2 v[134:135], v250, vcc
	s_add_u32 vcc_lo, s14, 0x5000
	s_addc_u32 vcc_hi, s15, 0
	global_load_dwordx2 v[136:137], v250, vcc
	s_add_u32 vcc_lo, s14, 0x6000
	s_addc_u32 vcc_hi, s15, 0
	global_load_dwordx2 v[138:139], v250, vcc
	s_add_u32 vcc_lo, s14, 0x7000
	s_addc_u32 vcc_hi, s15, 0
	global_load_dwordx2 v[140:141], v250, vcc
	s_add_u32 vcc_lo, s14, 0x8000
	s_addc_u32 vcc_hi, s15, 0
	global_load_dwordx2 v[142:143], v250, vcc
	s_add_u32 vcc_lo, s14, 0x9000
	s_addc_u32 vcc_hi, s15, 0
	global_load_dwordx2 v[144:145], v250, vcc
	s_add_u32 vcc_lo, s14, 0xa000
	s_addc_u32 vcc_hi, s15, 0
	global_load_dwordx2 v[146:147], v250, vcc
	s_add_u32 vcc_lo, s14, 0xb000
	s_addc_u32 vcc_hi, s15, 0
	global_load_dwordx2 v[148:149], v250, vcc
	s_add_u32 vcc_lo, s14, 0xc000
	s_addc_u32 vcc_hi, s15, 0
	global_load_dwordx2 v[150:151], v250, vcc
	s_add_u32 vcc_lo, s14, 0xd000
	s_addc_u32 vcc_hi, s15, 0
	global_load_dwordx2 v[152:153], v250, vcc
	s_add_u32 vcc_lo, s14, 0xe000
	s_addc_u32 vcc_hi, s15, 0
	global_load_dwordx2 v[154:155], v250, vcc
	s_add_u32 vcc_lo, s14, 0xf000
	s_addc_u32 vcc_hi, s15, 0
	global_load_dwordx2 v[156:157], v250, vcc
	s_add_u32 vcc_lo, s14, 0x10000
	s_addc_u32 vcc_hi, s15, 0
	global_load_dwordx2 v[158:159], v250, vcc
	s_add_u32 vcc_lo, s14, 0x11000
	s_addc_u32 vcc_hi, s15, 0
	global_load_dwordx2 v[160:161], v250, vcc
	s_add_u32 vcc_lo, s14, 0x12000
	s_addc_u32 vcc_hi, s15, 0
	global_load_dwordx2 v[162:163], v250, vcc
	s_add_u32 vcc_lo, s14, 0x13000
	s_addc_u32 vcc_hi, s15, 0
	global_load_dwordx2 v[164:165], v250, vcc
	s_add_u32 vcc_lo, s14, 0x14000
	s_addc_u32 vcc_hi, s15, 0
	global_load_dwordx2 v[166:167], v250, vcc
	s_add_u32 vcc_lo, s14, 0x15000
	s_addc_u32 vcc_hi, s15, 0
	global_load_dwordx2 v[168:169], v250, vcc
	s_add_u32 vcc_lo, s14, 0x16000
	s_addc_u32 vcc_hi, s15, 0
	global_load_dwordx2 v[170:171], v250, vcc
	s_add_u32 vcc_lo, s14, 0x17000
	s_addc_u32 vcc_hi, s15, 0
	global_load_dwordx2 v[172:173], v250, vcc
	s_add_u32 vcc_lo, s14, 0x18000
	s_addc_u32 vcc_hi, s15, 0
	global_load_dwordx2 v[174:175], v250, vcc
	s_add_u32 vcc_lo, s14, 0x19000
	s_addc_u32 vcc_hi, s15, 0
	global_load_dwordx2 v[176:177], v250, vcc
	s_add_u32 vcc_lo, s14, 0x1a000
	s_addc_u32 vcc_hi, s15, 0
	global_load_dwordx2 v[178:179], v250, vcc
	s_add_u32 vcc_lo, s14, 0x1b000
	s_addc_u32 vcc_hi, s15, 0
	global_load_dwordx2 v[180:181], v250, vcc
	s_add_u32 vcc_lo, s14, 0x1c000
	s_addc_u32 vcc_hi, s15, 0
	global_load_dwordx2 v[182:183], v250, vcc
	s_add_u32 vcc_lo, s14, 0x1d000
	s_addc_u32 vcc_hi, s15, 0
	global_load_dwordx2 v[184:185], v250, vcc
	s_add_u32 vcc_lo, s14, 0x1e000
	s_addc_u32 vcc_hi, s15, 0
	global_load_dwordx2 v[186:187], v250, vcc
	global_load_dwordx2 v[188:189], v250, s[16:17]
	v_cmp_le_i32_e32 vcc, s38, v0
	v_mov_b32_e32 v36, 0
	v_mov_b32_e32 v37, 0
	v_mov_b32_e32 v38, 0
	v_mov_b32_e32 v39, 0
	v_mov_b32_e32 v32, 0
	v_mov_b32_e32 v33, 0
	v_mov_b32_e32 v34, 0
	v_mov_b32_e32 v35, 0
	s_and_saveexec_b64 s[26:27], vcc
	s_cbranch_execz .LBB0_520
	v_mov_b64_e32 v[2:3], s[62:63]
	v_mad_i64_i32 v[0:1], s[40:41], v0, s30, v[2:3]
	s_lshl_b32 s12, s37, 1
	v_lshl_add_u64 v[0:1], v[0:1], 0, s[12:13]
	v_mov_b32_e32 v49, v41
	v_lshl_add_u64 v[0:1], v[0:1], 0, v[48:49]
	global_load_dwordx4 v[32:35], v[0:1], off
	global_load_dwordx4 v[36:39], v[0:1], off offset:2048
